# adds: split-K rows of norm phases P3/P7 load 8 partials per batch; HGRN passA next-sub-chunk loads stay in flight (lbl loads first, counted wait)
# baseline (speedup 1.0000x reference)
; template <int XSRC, bool HAS_F, bool HAS_NEXT, bool SPLIT, int XDST  > ...
;     ...
;             if (SPLIT && row >= MP) {
; #pragma unroll
;                 for (int i = 0; i < 8; ++i) { const float* pr = part + (size_t)(row - MP) * DM + (i >> 1) * 512 + lane * 8 + (i & 1) * 4; f32x4 a = *(const f32x4*)pr;
; #pragma unroll
;                     for (int s = 1; s < 8; ++s) a = a + *(const f32x4*)(pr + (size_t)s * 1024 * DM);
;                     f[i] = a; __builtin_amdgcn_sched_barrier(0); } }
.LBB0_360:
	s_lshl_b64 s[16:17], s[4:5], 13
	v_lshl_add_u64 v[66:67], v[132:133], 0, s[16:17]
	s_mov_b32 s16, 0x800000
	s_mov_b32 s17, 0
	v_lshl_add_u64 v[68:69], v[66:67], 0, s[16:17]
	v_lshl_add_u64 v[70:71], v[68:69], 0, s[16:17]
	v_lshl_add_u64 v[72:73], v[70:71], 0, s[16:17]
	v_lshl_add_u64 v[74:75], v[72:73], 0, s[16:17]
	v_lshl_add_u64 v[76:77], v[74:75], 0, s[16:17]
	v_lshl_add_u64 v[78:79], v[76:77], 0, s[16:17]
	v_lshl_add_u64 v[80:81], v[78:79], 0, s[16:17]
	global_load_dwordx4 v[34:37], v[66:67], off
	global_load_dwordx4 v[38:41], v[68:69], off
	global_load_dwordx4 v[42:45], v[70:71], off
	global_load_dwordx4 v[46:49], v[72:73], off
	global_load_dwordx4 v[50:53], v[74:75], off
	global_load_dwordx4 v[54:57], v[76:77], off
	global_load_dwordx4 v[58:61], v[78:79], off
	global_load_dwordx4 v[62:65], v[80:81], off
	s_waitcnt vmcnt(6)
	v_pk_add_f32 v[84:85], v[36:37], v[40:41]
	v_pk_add_f32 v[82:83], v[34:35], v[38:39]
	s_waitcnt vmcnt(5)
	v_pk_add_f32 v[84:85], v[84:85], v[44:45]
	v_pk_add_f32 v[82:83], v[82:83], v[42:43]
	s_waitcnt vmcnt(4)
	v_pk_add_f32 v[84:85], v[84:85], v[48:49]
	v_pk_add_f32 v[82:83], v[82:83], v[46:47]
	s_waitcnt vmcnt(3)
	v_pk_add_f32 v[84:85], v[84:85], v[52:53]
	v_pk_add_f32 v[82:83], v[82:83], v[50:51]
	s_waitcnt vmcnt(2)
	v_pk_add_f32 v[84:85], v[84:85], v[56:57]
	v_pk_add_f32 v[82:83], v[82:83], v[54:55]
	s_waitcnt vmcnt(1)
	v_pk_add_f32 v[84:85], v[84:85], v[60:61]
	v_pk_add_f32 v[82:83], v[82:83], v[58:59]
	s_waitcnt vmcnt(0)
	v_pk_add_f32 v[84:85], v[84:85], v[64:65]
	v_pk_add_f32 v[82:83], v[82:83], v[62:63]
	global_load_dwordx4 v[34:37], v[66:67], off offset:16
	global_load_dwordx4 v[38:41], v[68:69], off offset:16
	global_load_dwordx4 v[42:45], v[70:71], off offset:16
	global_load_dwordx4 v[46:49], v[72:73], off offset:16
	global_load_dwordx4 v[50:53], v[74:75], off offset:16
	global_load_dwordx4 v[54:57], v[76:77], off offset:16
	global_load_dwordx4 v[58:61], v[78:79], off offset:16
	global_load_dwordx4 v[62:65], v[80:81], off offset:16
	s_waitcnt vmcnt(6)
	v_pk_add_f32 v[88:89], v[36:37], v[40:41]
	v_pk_add_f32 v[86:87], v[34:35], v[38:39]
	s_waitcnt vmcnt(5)
	v_pk_add_f32 v[88:89], v[88:89], v[44:45]
	v_pk_add_f32 v[86:87], v[86:87], v[42:43]
	s_waitcnt vmcnt(4)
	v_pk_add_f32 v[88:89], v[88:89], v[48:49]
	v_pk_add_f32 v[86:87], v[86:87], v[46:47]
	s_waitcnt vmcnt(3)
	v_pk_add_f32 v[88:89], v[88:89], v[52:53]
	v_pk_add_f32 v[86:87], v[86:87], v[50:51]
	s_waitcnt vmcnt(2)
	v_pk_add_f32 v[88:89], v[88:89], v[56:57]
	v_pk_add_f32 v[86:87], v[86:87], v[54:55]
	s_waitcnt vmcnt(1)
	v_pk_add_f32 v[88:89], v[88:89], v[60:61]
	v_pk_add_f32 v[86:87], v[86:87], v[58:59]
	s_waitcnt vmcnt(0)
	v_pk_add_f32 v[88:89], v[88:89], v[64:65]
	v_pk_add_f32 v[86:87], v[86:87], v[62:63]
	global_load_dwordx4 v[34:37], v[66:67], off offset:2048
	global_load_dwordx4 v[38:41], v[68:69], off offset:2048
	global_load_dwordx4 v[42:45], v[70:71], off offset:2048
	global_load_dwordx4 v[46:49], v[72:73], off offset:2048
	global_load_dwordx4 v[50:53], v[74:75], off offset:2048
	global_load_dwordx4 v[54:57], v[76:77], off offset:2048
	global_load_dwordx4 v[58:61], v[78:79], off offset:2048
	global_load_dwordx4 v[62:65], v[80:81], off offset:2048
	s_waitcnt vmcnt(6)
	v_pk_add_f32 v[92:93], v[36:37], v[40:41]
	v_pk_add_f32 v[90:91], v[34:35], v[38:39]
	s_waitcnt vmcnt(5)
	v_pk_add_f32 v[92:93], v[92:93], v[44:45]
	v_pk_add_f32 v[90:91], v[90:91], v[42:43]
	s_waitcnt vmcnt(4)
	v_pk_add_f32 v[92:93], v[92:93], v[48:49]
	v_pk_add_f32 v[90:91], v[90:91], v[46:47]
	s_waitcnt vmcnt(3)
	v_pk_add_f32 v[92:93], v[92:93], v[52:53]
	v_pk_add_f32 v[90:91], v[90:91], v[50:51]
	s_waitcnt vmcnt(2)
	v_pk_add_f32 v[92:93], v[92:93], v[56:57]
	v_pk_add_f32 v[90:91], v[90:91], v[54:55]
	s_waitcnt vmcnt(1)
	v_pk_add_f32 v[92:93], v[92:93], v[60:61]
	v_pk_add_f32 v[90:91], v[90:91], v[58:59]
	s_waitcnt vmcnt(0)
	v_pk_add_f32 v[92:93], v[92:93], v[64:65]
	v_pk_add_f32 v[90:91], v[90:91], v[62:63]
	global_load_dwordx4 v[34:37], v[66:67], off offset:2064
	global_load_dwordx4 v[38:41], v[68:69], off offset:2064
	global_load_dwordx4 v[42:45], v[70:71], off offset:2064
	global_load_dwordx4 v[46:49], v[72:73], off offset:2064
	global_load_dwordx4 v[50:53], v[74:75], off offset:2064
	global_load_dwordx4 v[54:57], v[76:77], off offset:2064
	global_load_dwordx4 v[58:61], v[78:79], off offset:2064
	global_load_dwordx4 v[62:65], v[80:81], off offset:2064
	s_waitcnt vmcnt(6)
	v_pk_add_f32 v[96:97], v[36:37], v[40:41]
	v_pk_add_f32 v[94:95], v[34:35], v[38:39]
	s_waitcnt vmcnt(5)
	v_pk_add_f32 v[96:97], v[96:97], v[44:45]
	v_pk_add_f32 v[94:95], v[94:95], v[42:43]
	s_waitcnt vmcnt(4)
	v_pk_add_f32 v[96:97], v[96:97], v[48:49]
	v_pk_add_f32 v[94:95], v[94:95], v[46:47]
	s_waitcnt vmcnt(3)
	v_pk_add_f32 v[96:97], v[96:97], v[52:53]
	v_pk_add_f32 v[94:95], v[94:95], v[50:51]
	s_waitcnt vmcnt(2)
	v_pk_add_f32 v[96:97], v[96:97], v[56:57]
	v_pk_add_f32 v[94:95], v[94:95], v[54:55]
	s_waitcnt vmcnt(1)
	v_pk_add_f32 v[96:97], v[96:97], v[60:61]
	v_pk_add_f32 v[94:95], v[94:95], v[58:59]
	s_waitcnt vmcnt(0)
	v_pk_add_f32 v[96:97], v[96:97], v[64:65]
	v_pk_add_f32 v[94:95], v[94:95], v[62:63]
	s_movk_i32 s16, 0x1000
	v_lshl_add_u64 v[66:67], v[66:67], 0, s[16:17]
	v_lshl_add_u64 v[68:69], v[68:69], 0, s[16:17]
	v_lshl_add_u64 v[70:71], v[70:71], 0, s[16:17]
	v_lshl_add_u64 v[72:73], v[72:73], 0, s[16:17]
	v_lshl_add_u64 v[74:75], v[74:75], 0, s[16:17]
	v_lshl_add_u64 v[76:77], v[76:77], 0, s[16:17]
	v_lshl_add_u64 v[78:79], v[78:79], 0, s[16:17]
	v_lshl_add_u64 v[80:81], v[80:81], 0, s[16:17]
	global_load_dwordx4 v[34:37], v[66:67], off
	global_load_dwordx4 v[38:41], v[68:69], off
	global_load_dwordx4 v[42:45], v[70:71], off
	global_load_dwordx4 v[46:49], v[72:73], off
	global_load_dwordx4 v[50:53], v[74:75], off
	global_load_dwordx4 v[54:57], v[76:77], off
	global_load_dwordx4 v[58:61], v[78:79], off
	global_load_dwordx4 v[62:65], v[80:81], off
	s_waitcnt vmcnt(6)
; template <int XSRC, bool HAS_F, bool HAS_NEXT, bool SPLIT, int XDST  > ...
;     ...
;             if (SPLIT && row >= MP) {
; #pragma unroll
;                 for (int i = 0; i < 8; ++i) { const float* pr = part + (size_t)(row - MP) * DM + (i >> 1) * 512 + lane * 8 + (i & 1) * 4; f32x4 a = *(const f32x4*)pr;
; #pragma unroll
;                     for (int s = 1; s < 8; ++s) a = a + *(const f32x4*)(pr + (size_t)s * 1024 * DM);
;                     f[i] = a; __builtin_amdgcn_sched_barrier(0); } }
	v_pk_add_f32 v[100:101], v[36:37], v[40:41]
	v_pk_add_f32 v[98:99], v[34:35], v[38:39]
	s_waitcnt vmcnt(5)
	v_pk_add_f32 v[100:101], v[100:101], v[44:45]
	v_pk_add_f32 v[98:99], v[98:99], v[42:43]
	s_waitcnt vmcnt(4)
	v_pk_add_f32 v[100:101], v[100:101], v[48:49]
	v_pk_add_f32 v[98:99], v[98:99], v[46:47]
	s_waitcnt vmcnt(3)
	v_pk_add_f32 v[100:101], v[100:101], v[52:53]
	v_pk_add_f32 v[98:99], v[98:99], v[50:51]
	s_waitcnt vmcnt(2)
	v_pk_add_f32 v[100:101], v[100:101], v[56:57]
	v_pk_add_f32 v[98:99], v[98:99], v[54:55]
	s_waitcnt vmcnt(1)
	v_pk_add_f32 v[100:101], v[100:101], v[60:61]
	v_pk_add_f32 v[98:99], v[98:99], v[58:59]
	s_waitcnt vmcnt(0)
	v_pk_add_f32 v[100:101], v[100:101], v[64:65]
	v_pk_add_f32 v[98:99], v[98:99], v[62:63]
	global_load_dwordx4 v[34:37], v[66:67], off offset:16
	global_load_dwordx4 v[38:41], v[68:69], off offset:16
	global_load_dwordx4 v[42:45], v[70:71], off offset:16
	global_load_dwordx4 v[46:49], v[72:73], off offset:16
	global_load_dwordx4 v[50:53], v[74:75], off offset:16
	global_load_dwordx4 v[54:57], v[76:77], off offset:16
	global_load_dwordx4 v[58:61], v[78:79], off offset:16
	global_load_dwordx4 v[62:65], v[80:81], off offset:16
	s_waitcnt vmcnt(6)
	v_pk_add_f32 v[112:113], v[36:37], v[40:41]
	v_pk_add_f32 v[110:111], v[34:35], v[38:39]
	s_waitcnt vmcnt(5)
	v_pk_add_f32 v[112:113], v[112:113], v[44:45]
	v_pk_add_f32 v[110:111], v[110:111], v[42:43]
	s_waitcnt vmcnt(4)
	v_pk_add_f32 v[112:113], v[112:113], v[48:49]
	v_pk_add_f32 v[110:111], v[110:111], v[46:47]
	s_waitcnt vmcnt(3)
	v_pk_add_f32 v[112:113], v[112:113], v[52:53]
	v_pk_add_f32 v[110:111], v[110:111], v[50:51]
	s_waitcnt vmcnt(2)
	v_pk_add_f32 v[112:113], v[112:113], v[56:57]
	v_pk_add_f32 v[110:111], v[110:111], v[54:55]
	s_waitcnt vmcnt(1)
	v_pk_add_f32 v[112:113], v[112:113], v[60:61]
	v_pk_add_f32 v[110:111], v[110:111], v[58:59]
	s_waitcnt vmcnt(0)
	v_pk_add_f32 v[112:113], v[112:113], v[64:65]
	v_pk_add_f32 v[110:111], v[110:111], v[62:63]
	global_load_dwordx4 v[34:37], v[66:67], off offset:2048
	global_load_dwordx4 v[38:41], v[68:69], off offset:2048
	global_load_dwordx4 v[42:45], v[70:71], off offset:2048
	global_load_dwordx4 v[46:49], v[72:73], off offset:2048
	global_load_dwordx4 v[50:53], v[74:75], off offset:2048
	global_load_dwordx4 v[54:57], v[76:77], off offset:2048
	global_load_dwordx4 v[58:61], v[78:79], off offset:2048
	global_load_dwordx4 v[62:65], v[80:81], off offset:2048
	s_waitcnt vmcnt(6)
	v_pk_add_f32 v[124:125], v[36:37], v[40:41]
	v_pk_add_f32 v[122:123], v[34:35], v[38:39]
	s_waitcnt vmcnt(5)
	v_pk_add_f32 v[124:125], v[124:125], v[44:45]
	v_pk_add_f32 v[122:123], v[122:123], v[42:43]
	s_waitcnt vmcnt(4)
	v_pk_add_f32 v[124:125], v[124:125], v[48:49]
	v_pk_add_f32 v[122:123], v[122:123], v[46:47]
	s_waitcnt vmcnt(3)
	v_pk_add_f32 v[124:125], v[124:125], v[52:53]
	v_pk_add_f32 v[122:123], v[122:123], v[50:51]
	s_waitcnt vmcnt(2)
	v_pk_add_f32 v[124:125], v[124:125], v[56:57]
	v_pk_add_f32 v[122:123], v[122:123], v[54:55]
	s_waitcnt vmcnt(1)
	v_pk_add_f32 v[124:125], v[124:125], v[60:61]
	v_pk_add_f32 v[122:123], v[122:123], v[58:59]
	s_waitcnt vmcnt(0)
	v_pk_add_f32 v[124:125], v[124:125], v[64:65]
	v_pk_add_f32 v[122:123], v[122:123], v[62:63]
	global_load_dwordx4 v[34:37], v[66:67], off offset:2064
	global_load_dwordx4 v[38:41], v[68:69], off offset:2064
	global_load_dwordx4 v[42:45], v[70:71], off offset:2064
	global_load_dwordx4 v[46:49], v[72:73], off offset:2064
	global_load_dwordx4 v[50:53], v[74:75], off offset:2064
	global_load_dwordx4 v[54:57], v[76:77], off offset:2064
	global_load_dwordx4 v[58:61], v[78:79], off offset:2064
	global_load_dwordx4 v[62:65], v[80:81], off offset:2064
	s_waitcnt vmcnt(6)
	v_pk_add_f32 v[128:129], v[36:37], v[40:41]
	v_pk_add_f32 v[126:127], v[34:35], v[38:39]
	s_waitcnt vmcnt(5)
	v_pk_add_f32 v[128:129], v[128:129], v[44:45]
	v_pk_add_f32 v[126:127], v[126:127], v[42:43]
	s_waitcnt vmcnt(4)
	v_pk_add_f32 v[128:129], v[128:129], v[48:49]
	v_pk_add_f32 v[126:127], v[126:127], v[46:47]
	s_waitcnt vmcnt(3)
	v_pk_add_f32 v[128:129], v[128:129], v[52:53]
	v_pk_add_f32 v[126:127], v[126:127], v[50:51]
	s_waitcnt vmcnt(2)
	v_pk_add_f32 v[128:129], v[128:129], v[56:57]
	v_pk_add_f32 v[126:127], v[126:127], v[54:55]
	s_waitcnt vmcnt(1)
	v_pk_add_f32 v[128:129], v[128:129], v[60:61]
	v_pk_add_f32 v[126:127], v[126:127], v[58:59]
	s_waitcnt vmcnt(0)
	v_pk_add_f32 v[128:129], v[128:129], v[64:65]
	v_pk_add_f32 v[126:127], v[126:127], v[62:63]
	v_mov_b64_e32 v[34:35], 0
	v_mov_b64_e32 v[36:37], 0
	v_mov_b64_e32 v[38:39], 0
	v_mov_b64_e32 v[40:41], 0
	v_mov_b64_e32 v[42:43], 0
	v_mov_b64_e32 v[44:45], 0
	v_mov_b64_e32 v[46:47], 0
	v_mov_b64_e32 v[48:49], 0
	v_mov_b64_e32 v[50:51], 0
	v_mov_b64_e32 v[52:53], 0
	v_mov_b64_e32 v[54:55], 0
	v_mov_b64_e32 v[56:57], 0
	v_mov_b64_e32 v[58:59], 0
	v_mov_b64_e32 v[60:61], 0
	v_mov_b64_e32 v[62:63], 0
	v_mov_b64_e32 v[64:65], 0
	v_mov_b64_e32 v[66:67], 0
	v_mov_b64_e32 v[68:69], 0
	v_mov_b64_e32 v[70:71], 0
	v_mov_b64_e32 v[72:73], 0
	v_mov_b64_e32 v[74:75], 0
	v_mov_b64_e32 v[76:77], 0
	v_mov_b64_e32 v[78:79], 0
	v_mov_b64_e32 v[80:81], 0
	s_branch .LBB0_352

; __device__ __forceinline__ void hgrn_passA_load(PassARaw& R, int u, const bf16* Z, int tid) {
;     const int c = u & 63, h = (u >> 6) & 7, b = u >> 9; const int chp = tid & 63, tq8 = tid >> 6;
;     const bf16* zr = Z + ((size_t)b * SEQ + c * 64 + tq8 * 8) * NIN + h * 128 + chp * 2;
; #pragma unroll
;     for (int i = 0; i < 8; ++i) { R.f[i] = *(const unsigned*)(zr + (size_t)i * NIN + ZHF); R.q[i] = *(const unsigned*)(zr + (size_t)i * NIN + ZHQ); R.v[i] = *(const unsigned*)(zr + (size_t)i * NIN + ZHI); }
; __global__ void __launch_bounds__(512, 2) mega_fwd(Params p) {
;     ...
;       int U = bx, j = 0;
;       if (U < 512) hgrn_passA_load(Rc, (U >> 4) * 64 + (U & 15) * 4, Z, tid);
.LBB0_568:
	s_or_b64 exec, exec, s[0:1]
	s_add_u32 s0, s92, 0x21700000
	s_addc_u32 s1, s93, 0
	v_writelane_b32 v255, s0, 34
	s_waitcnt lgkmcnt(0)
	s_barrier
	v_writelane_b32 v255, s1, 35
	s_add_u32 s0, s92, 0x23700000
	s_addc_u32 s1, s93, 0
	v_writelane_b32 v255, s0, 36
	s_cmpk_lt_i32 s71, 0x200
	s_cselect_b64 s[2:3], -1, 0
	v_writelane_b32 v255, s1, 37
	v_writelane_b32 v255, s2, 38
	s_cmpk_gt_i32 s71, 0x1ff
	s_nop 0
	v_writelane_b32 v255, s3, 39
	s_cbranch_scc1 .LBB0_590
	s_ashr_i32 s0, s71, 7
	s_ashr_i32 s1, s0, 31
	s_lshl_b32 s2, s71, 8
	s_lshl_b64 s[0:1], s[0:1], 12
	s_and_b32 s2, s2, 0xf00
	v_readlane_b32 s4, v255, 0
	s_or_b32 s0, s0, s2
	v_and_b32_e32 v63, 0x78, v141
	v_readlane_b32 s5, v255, 1
	v_or_b32_e32 v4, s0, v63
	s_movk_i32 s3, 0x2c00
	v_mov_b64_e32 v[2:3], s[4:5]
	v_mad_u64_u32 v[2:3], s[4:5], v4, s3, v[2:3]
	v_mov_b32_e32 v4, 0x2c00
	v_mad_i32_i24 v3, s1, v4, v3
	s_and_b32 s0, s52, 0x380
	v_lshlrev_b32_e32 v4, 1, v1
	s_lshl_b32 s38, s0, 1
	s_mov_b32 s39, 0
	v_and_b32_e32 v62, 0x7e, v4
	v_lshl_add_u64 v[2:3], v[2:3], 0, s[38:39]
	v_mov_b32_e32 v65, 0
	v_lshlrev_b32_e32 v64, 1, v62
	v_lshl_add_u64 v[2:3], v[2:3], 0, v[64:65]
	s_movk_i32 s50, 0x1000
	v_add_co_u32_e32 v4, vcc, s50, v2
	s_movk_i32 s0, 0x4000
	s_nop 0
	v_addc_co_u32_e32 v5, vcc, 0, v3, vcc
	v_add_co_u32_e32 v6, vcc, s0, v2
	s_movk_i32 s70, 0x3000
	s_nop 0
	v_addc_co_u32_e32 v7, vcc, 0, v3, vcc
	v_add_co_u32_e32 v8, vcc, s70, v2
	s_movk_i32 s77, 0x6000
	s_nop 0
	v_addc_co_u32_e32 v9, vcc, 0, v3, vcc
	v_add_co_u32_e32 v10, vcc, s77, v2
	s_movk_i32 s0, 0x7000
	s_nop 0
	v_addc_co_u32_e32 v11, vcc, 0, v3, vcc
	global_load_dword v38, v[4:5], off offset:1024
	global_load_dword v122, v[4:5], off offset:3072
	global_load_dword v39, v[6:7], off
	global_load_dword v35, v[8:9], off offset:2048
	global_load_dword v43, v[10:11], off offset:3072
	global_load_dword v42, v[10:11], off offset:1024
	global_load_dword v119, v[6:7], off offset:2048
	global_load_dword v34, v[2:3], off offset:3072
	v_add_co_u32_e32 v4, vcc, s0, v2
	s_mov_b32 s97, 0x9000
	s_nop 0
	v_addc_co_u32_e32 v5, vcc, 0, v3, vcc
	v_add_co_u32_e32 v6, vcc, s97, v2
	s_mov_b32 s51, 0xa000
	s_nop 0
	v_addc_co_u32_e32 v7, vcc, 0, v3, vcc
	v_add_co_u32_e32 v8, vcc, s51, v2
	s_mov_b32 s0, 0xc000
	s_nop 0
	v_addc_co_u32_e32 v9, vcc, 0, v3, vcc
	v_add_co_u32_e32 v10, vcc, s0, v2
	s_mov_b32 s33, 0xb000
	s_nop 0
	v_addc_co_u32_e32 v11, vcc, 0, v3, vcc
	v_add_co_u32_e32 v12, vcc, s33, v2
	s_mov_b32 s2, 0xf000
	s_nop 0
	v_addc_co_u32_e32 v13, vcc, 0, v3, vcc
	v_add_co_u32_e32 v14, vcc, s2, v2
	s_mov_b32 s0, 0xe000
	s_nop 0
	v_addc_co_u32_e32 v15, vcc, 0, v3, vcc
	v_add_co_u32_e32 v16, vcc, s0, v2
	s_mov_b32 s0, 0x11000
	s_nop 0
	v_addc_co_u32_e32 v17, vcc, 0, v3, vcc
	global_load_dword v125, v[4:5], off offset:1024
	global_load_dword v47, v[6:7], off offset:2048
	global_load_dword v40, v[10:11], off offset:1024
	global_load_dword v36, v[12:13], off offset:3072
	global_load_dword v41, v[14:15], off
	global_load_dword v37, v[16:17], off offset:2048
	global_load_dword v201, v[14:15], off offset:2048
	global_load_dword v202, v[10:11], off offset:3072
	v_add_co_u32_e32 v4, vcc, s0, v2
	s_mov_b32 s0, 0x12000
	s_nop 0
	v_addc_co_u32_e32 v5, vcc, 0, v3, vcc
	v_add_co_u32_e32 v6, vcc, s0, v2
	s_mov_b32 s0, 0x14000
	s_nop 0
	v_addc_co_u32_e32 v7, vcc, 0, v3, vcc
	v_add_co_u32_e32 v10, vcc, s0, v2
	s_mov_b32 s0, 0x15000
	s_nop 0
	v_addc_co_u32_e32 v11, vcc, 0, v3, vcc
	v_add_co_u32_e32 v2, vcc, s0, v2
	s_movk_i32 s0, 0x7f
	s_nop 0
	v_addc_co_u32_e32 v3, vcc, 0, v3, vcc
	global_load_dword v50, v[8:9], off offset:-4096
	global_load_dword v203, v[8:9], off
	global_load_dword v49, v[4:5], off offset:3072
	global_load_dword v200, v[6:7], off offset:1024
	global_load_dword v44, v[2:3], off offset:-4096
	global_load_dword v93, v[2:3], off
	global_load_dword v45, v[10:11], off offset:2048
	global_load_dword v48, v[4:5], off offset:1024
	v_readlane_b32 s8, v255, 36
	v_cmp_lt_u32_e64 s[6:7], s0, v1
	s_movk_i32 s0, 0xbf
	v_readlane_b32 s9, v255, 37
	v_cmp_lt_u32_e64 s[66:67], s0, v1
	s_movk_i32 s0, 0xff
	v_lshl_add_u64 v[68:69], s[8:9], 0, v[64:65]
	v_readlane_b32 s8, v254, 23
	v_lshrrev_b32_e32 v2, 6, v1
	v_lshl_add_u32 v128, v62, 2, 0
	v_cmp_lt_u32_e64 s[68:69], s0, v1
	s_movk_i32 s0, 0x13f
	s_lshl_b32 s20, s8, 3
	v_lshl_add_u32 v129, v2, 9, v128
	v_cmp_lt_u32_e64 s[72:73], s0, v1
	s_movk_i32 s0, 0x17f
	v_lshlrev_b32_e32 v66, 3, v2
	v_mul_u32_u24_e32 v132, 0x880, v2
	v_lshl_add_u32 v3, v2, 4, 0
	s_lshl_b32 s40, s8, 5
	s_and_b32 s20, s20, 0x1ffffff0
	v_and_b32_e32 v2, 12, v142
	v_cmp_lt_u32_e64 s[74:75], s0, v1
	s_movk_i32 s0, 0x1bf
	s_movk_i32 s1, 0x110
	v_or_b32_e32 v86, s20, v217
	v_or_b32_e32 v5, s20, v2
	v_and_or_b32 v6, s40, 32, v217
	v_cmp_lt_u32_e64 s[52:53], s0, v1
; #define LAS __attribute__((address_space(3)))
; __device__ __forceinline__ void hgrn_passA4_sub(int u, int j, const PassARaw& R, const bf16* Z, const float* lbl, bf16* QH, bf16* OI, f32x4 (&uc)[8], float (&Lbase)[2], LAS unsigned char* lds, int tid, int wave, int lane) {
;     constexpr int TOT = 0, QT = 4096, KT = QT + 64 * 272, KH = KT + 64 * 272, VT = KH + 128 * 144, AM = VT + 128 * 144, QL = AM + 64 * 144, UCT = QL + 64 * 272, DCL = UCT + 128 * 272;
;     const int c = u & 63, h = (u >> 6) & 7, b = u >> 9; const int fr = lane & 15, fq = lane >> 4;
;     const size_t r0 = (size_t)b * SEQ + c * 64;
;     const int chp = tid & 63, tq8 = tid >> 6, c0 = chp * 2;
; __global__ void __launch_bounds__(512, 2) mega_fwd(Params p) {
;     ...
;       while (U < 512) {
;           int Un = U, jn = j + 1; if (jn == 4) { jn = 0; Un = U + G; }
;           if (Un < 512) hgrn_passA_load(Rn, (Un >> 4) * 64 + (Un & 15) * 4 + jn, Z, tid);
;           if (j == 0) { Lbase[0] = 0.f; Lbase[1] = 0.f;
; #pragma unroll
;               for (int i = 0; i < 8; ++i) uc[i] = (f32x4){0.f, 0.f, 0.f, 0.f}; }
;           hgrn_passA4_sub((U >> 4) * 64 + (U & 15) * 4 + j, j, Rc, Z, p.in[17], QH, OI, uc, Lbase, lds, tid, wave, lane);
	s_movk_i32 s0, 0x1ff
	v_mul_lo_u32 v4, v86, s1
	v_mad_u32_u24 v135, v6, s1, 0
	s_add_i32 s1, 0, 0x12800
	v_or_b32_e32 v7, 1, v5
	v_or_b32_e32 v12, 2, v5
	v_or_b32_e32 v13, 3, v5
	v_cmp_lt_u32_e64 s[54:55], s0, v1
	s_add_i32 s0, 0, 0x14c00
	v_lshl_add_u32 v10, v6, 1, s1
	v_cmp_gt_u32_e64 s[56:57], v6, v5
	v_cmp_gt_u32_e64 s[58:59], v6, v7
	v_cmp_gt_u32_e64 s[24:25], v6, v12
	v_cmp_gt_u32_e64 s[26:27], v6, v13
	v_or_b32_e32 v6, 16, v6
	v_add_u32_e32 v131, s0, v64
	v_cmp_gt_u32_e64 s[36:37], v6, v13
	v_add_u32_e32 v13, s0, v4
	v_readlane_b32 s0, v254, 3
	s_movk_i32 s38, 0x90
	s_and_b32 s41, s0, 64
	v_add_u32_e32 v9, 0, v4
	v_mul_lo_u32 v11, v5, s38
	v_cmp_gt_u32_e64 s[28:29], v6, v5
	v_mul_lo_u32 v5, v86, s38
	v_or_b32_e32 v4, s41, v217
	v_cmp_gt_u32_e64 s[34:35], v6, v12
	v_add_u32_e32 v12, s1, v5
	v_or_b32_e32 v5, 16, v4
	v_lshl_add_u32 v15, v6, 1, s1
	v_mul_u32_u24_e32 v18, 0x90, v4
	v_mul_u32_u24_e32 v19, 0x110, v4
	v_mul_u32_u24_e32 v20, 0x90, v5
	v_mul_u32_u24_e32 v21, 0x110, v5
	v_or_b32_e32 v5, 32, v4
	v_or_b32_e32 v4, 48, v4
	s_lshl_b32 s1, s8, 4
	v_mul_u32_u24_e32 v24, 0x90, v4
	v_mul_u32_u24_e32 v25, 0x110, v4
	v_or_b32_e32 v4, s1, v217
	v_mul_lo_u32 v4, v4, s38
	v_and_b32_e32 v134, 48, v1
	s_add_i32 s0, 0, 0x19000
	v_add_u32_e32 v26, 0, v4
	v_or_b32_e32 v4, s1, v2
	v_add_u32_e32 v17, s0, v134
	v_lshl_add_u32 v32, v4, 1, s0
	v_readlane_b32 s0, v255, 16
	v_cmp_gt_u32_e64 s[30:31], v6, v7
	v_mov_b32_e32 v6, 0x2400
	v_readlane_b32 s1, v255, 17
	s_add_u32 s0, s0, s40
	v_sub_u32_e32 v130, v128, v64
	v_lshlrev_b32_e32 v84, 3, v1
	v_mul_u32_u24_e32 v22, 0x90, v5
	v_mul_u32_u24_e32 v23, 0x110, v5
	v_or_b32_e32 v5, 48, v165
	v_mad_u32_u24 v30, v217, s38, v6
	v_or_b32_e32 v6, 0x70, v165
	s_addc_u32 s1, s1, 0
	v_lshlrev_b32_e32 v64, 1, v2
	v_mov_b32_e32 v85, v65
	v_lshlrev_b32_e32 v27, 2, v4
	v_mul_u32_u24_e32 v29, 0x90, v5
	v_mul_u32_u24_e32 v31, 0x90, v6
	v_mul_u32_u24_e32 v46, 0x110, v5
	v_mul_u32_u24_e32 v51, 0x110, v6
	v_lshl_add_u64 v[4:5], s[0:1], 0, v[64:65]
	v_lshl_add_u64 v[6:7], s[92:93], 0, v[84:85]
	s_mov_b64 s[0:1], 0x6e00000
	v_lshl_add_u64 v[88:89], v[6:7], 0, s[0:1]
	v_lshlrev_b32_e32 v6, 8, v1
	v_or_b32_e32 v70, 1, v66
	v_mul_u32_u24_e32 v8, 0x90, v62
	v_add_u32_e32 v14, 0x1100, v135
	v_add_u32_e32 v16, 0, v134
	v_mul_u32_u24_e32 v28, 0x90, v217
	v_mul_u32_u24_e32 v33, 0x110, v217
	v_and_b32_e32 v64, 0xf00, v6
	v_lshlrev_b32_e32 v92, 1, v2
	v_add_u32_e32 v2, 0, v27
	v_cmp_gt_u32_e64 s[4:5], 64, v1
	v_mov_b32_e32 v67, v65
	v_mul_u32_u24_e32 v133, 0x110, v70
	v_mov_b32_e32 v71, v65
	v_or_b32_e32 v72, 2, v66
	v_mov_b32_e32 v73, v65
	v_or_b32_e32 v74, 3, v66
	v_mov_b32_e32 v75, v65
	v_or_b32_e32 v76, 4, v66
	v_mov_b32_e32 v77, v65
	v_or_b32_e32 v78, 5, v66
	v_mov_b32_e32 v79, v65
	v_or_b32_e32 v80, 6, v66
	v_mov_b32_e32 v81, v65
	v_or_b32_e32 v82, 7, v66
	v_mov_b32_e32 v83, v65
	v_mov_b32_e32 v87, v65
	v_lshl_add_u64 v[90:91], v[4:5], 0, v[64:65]
	s_mov_b32 s60, 0xffff0000
	s_mov_b32 s61, 0x800000
	s_mov_b32 s62, 0x3f317217
	s_mov_b32 s63, 0x7f800000
	v_add_u32_e32 v85, v3, v8
	v_add_u32_e32 v136, v9, v134
	v_add_u32_e32 v137, v10, v11
	v_add_u32_e32 v138, v14, v134
	v_add_u32_e32 v139, v15, v11
	v_add_u32_e32 v143, v12, v134
	v_add_u32_e32 v144, v13, v134
	v_add_u32_e32 v145, v16, v18
	v_add_u32_e32 v146, v17, v19
	s_lshl_b32 s40, s41, 1
	v_add_u32_e32 v147, v16, v20
	v_add_u32_e32 v148, v17, v21
	v_add_u32_e32 v149, v16, v22
	v_add_u32_e32 v150, v17, v23
	v_add_u32_e32 v151, v16, v24
	v_add_u32_e32 v152, v17, v25
	v_add_u32_e32 v153, v26, v134
	v_add_u32_e32 v154, 0x21800, v2
	v_add_u32_e32 v155, v16, v28
	v_add_u32_e32 v156, v16, v29
	v_add_u32_e32 v157, v16, v30
	v_add_u32_e32 v158, v16, v31
	v_add_u32_e32 v159, v32, v33
	v_add_u32_e32 v160, v32, v46
	v_add_u32_e32 v161, v32, v51
	v_mov_b32_e32 v167, 0x41b17218
	s_mov_b32 s42, s71
	s_mov_b32 s43, 0
	v_mov_b32_e32 v2, v65
	v_mov_b32_e32 v3, v65
	v_mov_b32_e32 v4, v65
	v_mov_b32_e32 v5, v65
	v_mov_b32_e32 v6, v65
	v_mov_b32_e32 v7, v65
	v_mov_b32_e32 v8, v65
	v_mov_b32_e32 v9, v65
	v_mov_b32_e32 v10, v65
	v_mov_b32_e32 v11, v65
	v_mov_b32_e32 v12, v65
	v_mov_b32_e32 v13, v65
	v_mov_b32_e32 v14, v65
	v_mov_b32_e32 v15, v65
	v_mov_b32_e32 v16, v65
	v_mov_b32_e32 v17, v65
	v_mov_b32_e32 v22, v65
	v_mov_b32_e32 v23, v65
	v_mov_b32_e32 v24, v65
	v_mov_b32_e32 v25, v65
	v_mov_b32_e32 v18, v65
	v_mov_b32_e32 v19, v65
	v_mov_b32_e32 v20, v65
	v_mov_b32_e32 v21, v65
	v_mov_b32_e32 v30, v65
	v_mov_b32_e32 v31, v65
	v_mov_b32_e32 v32, v65
	v_mov_b32_e32 v33, v65
	v_mov_b32_e32 v26, v65
	v_mov_b32_e32 v27, v65
	v_mov_b32_e32 v28, v65
	v_mov_b32_e32 v29, v65
	v_mov_b32_e32 v94, v65
	v_mov_b32_e32 v95, v65
	s_waitcnt vmcnt(0)
	s_branch .LBB0_572
.Lpa_noprefetch:
	s_waitcnt vmcnt(0)
	s_branch .LBB0_574

; __device__ __forceinline__ unsigned pk2(float lo, float hi) { f32x2 v = {lo, hi}; bf16x2_t b = __builtin_convertvector(v, bf16x2_t); return __builtin_bit_cast(unsigned, b); }
; __device__ __forceinline__ void hgrn_passA_load(PassARaw& R, int u, const bf16* Z, int tid) {
;     const int c = u & 63, h = (u >> 6) & 7, b = u >> 9; const int chp = tid & 63, tq8 = tid >> 6;
;     const bf16* zr = Z + ((size_t)b * SEQ + c * 64 + tq8 * 8) * NIN + h * 128 + chp * 2;
; #pragma unroll
;     for (int i = 0; i < 8; ++i) { R.f[i] = *(const unsigned*)(zr + (size_t)i * NIN + ZHF); R.q[i] = *(const unsigned*)(zr + (size_t)i * NIN + ZHQ); R.v[i] = *(const unsigned*)(zr + (size_t)i * NIN + ZHI); }
; __device__ __forceinline__ void hgrn_passA4_sub(int u, int j, const PassARaw& R, const bf16* Z, const float* lbl, bf16* QH, bf16* OI, f32x4 (&uc)[8], float (&Lbase)[2], LAS unsigned char* lds, int tid, int wave, int lane) {
;     ...
;         for (int cc = 0; cc < 2; ++cc) { const float l0 = lbl[h * 128 + c0 + cc], l1 = lbl[1024 + h * 128 + c0 + cc]; lb[cc] = 1.0f / (1.0f + __expf(l1 - l0)); omlb[cc] = 1.0f - lb[cc]; }
; __global__ void __launch_bounds__(512, 2) mega_fwd(Params p) {
;     ...
;       while (U < 512) {
;           int Un = U, jn = j + 1; if (jn == 4) { jn = 0; Un = U + G; }
;           if (Un < 512) hgrn_passA_load(Rn, (Un >> 4) * 64 + (Un & 15) * 4 + jn, Z, tid);
;           if (j == 0) { Lbase[0] = 0.f; Lbase[1] = 0.f;
; #pragma unroll
;               for (int i = 0; i < 8; ++i) uc[i] = (f32x4){0.f, 0.f, 0.f, 0.f}; }
;           hgrn_passA4_sub((U >> 4) * 64 + (U & 15) * 4 + j, j, Rc, Z, p.in[17], QH, OI, uc, Lbase, lds, tid, wave, lane);
;           if (j == 3) { const int fr = lane & 15, fq = lane >> 4;
; #pragma unroll
;               for (int dvt = 0; dvt < 8; ++dvt) *(u32x2*)(UT + (size_t)U * 16384 + (dvt * 16 + fr) * 128 + wave * 16 + fq * 4) = (u32x2){pk2(uc[dvt][0], uc[dvt][1]), pk2(uc[dvt][2], uc[dvt][3])};
;               if (tid < 64) { DC[(size_t)U * 128 + 2 * tid] = __expf(Lbase[0]); DC[(size_t)U * 128 + 2 * tid + 1] = __expf(Lbase[1]); } }
;           Rc = Rn; U = Un; j = jn; }
.LBB0_571:
	s_waitcnt vmcnt(0)
	s_andn2_b64 vcc, exec, s[44:45]
	s_mov_b32 s42, s65
	s_mov_b32 s43, s64
	v_mov_b32_e32 v93, v199
	v_mov_b32_e32 v200, v195
	v_mov_b32_e32 v201, v192
	v_mov_b32_e32 v202, v188
	v_mov_b32_e32 v203, v185
	v_mov_b32_e32 v125, v182
	v_mov_b32_e32 v119, v177
	v_mov_b32_e32 v122, v169
	v_mov_b32_e32 v44, v197
	v_mov_b32_e32 v48, v194
	v_mov_b32_e32 v37, v193
	v_mov_b32_e32 v36, v189
	v_mov_b32_e32 v50, v186
	v_mov_b32_e32 v42, v183
	v_mov_b32_e32 v35, v180
	v_mov_b32_e32 v34, v171
	v_mov_b32_e32 v45, v198
	v_mov_b32_e32 v49, v196
	v_mov_b32_e32 v41, v191
	v_mov_b32_e32 v40, v190
	v_mov_b32_e32 v47, v187
	v_mov_b32_e32 v43, v184
	v_mov_b32_e32 v39, v181
	v_mov_b32_e32 v38, v173
	s_cbranch_vccz .LBB0_589
.LBB0_572:
	s_lshl_b32 s0, s42, 2
	s_add_i32 s0, s0, s43
	s_lshl_b32 s0, s0, 1
	s_and_b32 s0, s0, 0x380
	v_readlane_b32 s10, v254, 31
	v_readlane_b32 s11, v254, 32
	v_or_b32_e32 v204, s0, v62
	v_lshlrev_b32_e32 v204, 2, v204
	v_add_u32_e32 v206, 0x1000, v204
	s_nop 4
	global_load_dwordx2 v[204:205], v204, s[10:11]
	global_load_dwordx2 v[206:207], v206, s[10:11]
	s_add_i32 s0, s43, 1
	s_cmp_eq_u32 s0, 4
	s_cselect_b32 s65, s94, 0
	s_cselect_b32 s64, 0, s0
	s_add_i32 s65, s65, s42
	s_cmpk_gt_i32 s65, 0x1ff
	s_cselect_b64 s[44:45], -1, 0
	s_and_b64 vcc, exec, s[44:45]
	s_cbranch_vccnz .Lpa_noprefetch
	s_lshl_b32 s0, s65, 2
	s_add_i32 s38, s0, s64
	s_ashr_i32 s0, s38, 9
	s_lshl_b32 s41, s38, 6
	s_ashr_i32 s1, s0, 31
	s_and_b32 s41, s41, 0xfc0
	s_lshl_b64 s[0:1], s[0:1], 12
	v_add_u32_e32 v64, s41, v63
	v_lshl_add_u64 v[52:53], s[0:1], 0, v[64:65]
	v_readlane_b32 s0, v255, 0
	v_readlane_b32 s1, v255, 1
	v_lshlrev_b32_e32 v64, 1, v62
	s_nop 0
	v_mov_b64_e32 v[54:55], s[0:1]
	v_mad_u64_u32 v[54:55], s[0:1], v52, s3, v[54:55]
	s_lshl_b32 s0, s38, 2
	v_mad_i32_i24 v55, v53, s3, v55
	s_and_b32 s38, s0, 0x700
	v_lshl_add_u64 v[52:53], v[54:55], 0, s[38:39]
	v_lshl_add_u64 v[52:53], v[52:53], 0, v[64:65]
	v_add_co_u32_e32 v54, vcc, s50, v52
	s_movk_i32 s0, 0x4000
	s_nop 0
	v_addc_co_u32_e32 v55, vcc, 0, v53, vcc
	global_load_dword v173, v[54:55], off offset:1024
	global_load_dword v171, v[52:53], off offset:3072
	global_load_dword v169, v[54:55], off offset:3072
	v_add_co_u32_e32 v54, vcc, s0, v52
	s_movk_i32 s0, 0x7000
	s_nop 0
	v_addc_co_u32_e32 v55, vcc, 0, v53, vcc
	v_add_co_u32_e32 v56, vcc, s70, v52
	global_load_dword v181, v[54:55], off
	s_nop 0
	v_addc_co_u32_e32 v57, vcc, 0, v53, vcc
	global_load_dword v180, v[56:57], off offset:2048
	global_load_dword v177, v[54:55], off offset:2048
	v_add_co_u32_e32 v54, vcc, s77, v52
	s_nop 1
	v_addc_co_u32_e32 v55, vcc, 0, v53, vcc
	global_load_dword v184, v[54:55], off offset:3072
	global_load_dword v183, v[54:55], off offset:1024
	v_add_co_u32_e32 v54, vcc, s0, v52
	s_mov_b32 s0, 0xc000
	s_nop 0
	v_addc_co_u32_e32 v55, vcc, 0, v53, vcc
	global_load_dword v182, v[54:55], off offset:1024
	v_add_co_u32_e32 v54, vcc, s97, v52
	s_nop 1
	v_addc_co_u32_e32 v55, vcc, 0, v53, vcc
	global_load_dword v187, v[54:55], off offset:2048
	v_add_co_u32_e32 v54, vcc, s51, v52
	s_nop 1
	v_addc_co_u32_e32 v55, vcc, 0, v53, vcc
	global_load_dword v186, v[54:55], off offset:-4096
	global_load_dword v185, v[54:55], off
	v_add_co_u32_e32 v54, vcc, s0, v52
	s_mov_b32 s0, 0xe000
	s_nop 0
	v_addc_co_u32_e32 v55, vcc, 0, v53, vcc
	v_add_co_u32_e32 v56, vcc, s33, v52
	global_load_dword v190, v[54:55], off offset:1024
	s_nop 0
	v_addc_co_u32_e32 v57, vcc, 0, v53, vcc
	global_load_dword v189, v[56:57], off offset:3072
	global_load_dword v188, v[54:55], off offset:3072
	v_add_co_u32_e32 v54, vcc, s2, v52
	s_nop 1
	v_addc_co_u32_e32 v55, vcc, 0, v53, vcc
	v_add_co_u32_e32 v56, vcc, s0, v52
	s_mov_b32 s0, 0x11000
	s_nop 0
	v_addc_co_u32_e32 v57, vcc, 0, v53, vcc
	global_load_dword v191, v[54:55], off
	global_load_dword v193, v[56:57], off offset:2048
	global_load_dword v192, v[54:55], off offset:2048
	v_add_co_u32_e32 v54, vcc, s0, v52
	s_nop 1
	v_addc_co_u32_e32 v55, vcc, 0, v53, vcc
	global_load_dword v196, v[54:55], off offset:3072
	global_load_dword v194, v[54:55], off offset:1024
	v_add_co_u32_e32 v54, vcc, 0x12000, v52
	s_nop 1
	v_addc_co_u32_e32 v55, vcc, 0, v53, vcc
	global_load_dword v195, v[54:55], off offset:1024
	v_add_co_u32_e32 v54, vcc, 0x14000, v52
	s_nop 1
	v_addc_co_u32_e32 v55, vcc, 0, v53, vcc
	v_add_co_u32_e32 v52, vcc, 0x15000, v52
	global_load_dword v198, v[54:55], off offset:2048
	global_load_dword v197, v[54:55], off
	v_addc_co_u32_e32 v53, vcc, 0, v53, vcc
	global_load_dword v199, v[52:53], off

; __device__ __forceinline__ float bflo(unsigned w) { return __uint_as_float(w << 16); }
; __device__ __forceinline__ float bfhi(unsigned w) { return __uint_as_float(w & 0xffff0000u); }
; __device__ __forceinline__ float sigmoidf_(float x) { return __builtin_amdgcn_rcpf(1.0f + __expf(-x)); }
; __device__ __forceinline__ float siluf_(float x) { return x * sigmoidf_(x); }
; __device__ __forceinline__ void hgrn_passA4_sub(int u, int j, const PassARaw& R, const bf16* Z, const float* lbl, bf16* QH, bf16* OI, f32x4 (&uc)[8], float (&Lbase)[2], LAS unsigned char* lds, int tid, int wave, int lane) {
;     ...
;         for (int cc = 0; cc < 2; ++cc) { const float l0 = lbl[h * 128 + c0 + cc], l1 = lbl[1024 + h * 128 + c0 + cc]; lb[cc] = 1.0f / (1.0f + __expf(l1 - l0)); omlb[cc] = 1.0f - lb[cc]; }
;         float L[2][8], kk[2][8], qq[2][8]; float cum[2] = {0.f, 0.f};
; #pragma unroll
;         for (int i = 0; i < 8; ++i)
; #pragma unroll
;             for (int cc = 0; cc < 2; ++cc) { const float fraw = cc ? bfhi(R.f[i]) : bflo(R.f[i]), qraw = cc ? bfhi(R.q[i]) : bflo(R.q[i]);
;                 const float sg = sigmoidf_(fraw); cum[cc] += __logf(lb[cc] + omlb[cc] * sg); L[cc][i] = cum[cc]; kk[cc][i] = omlb[cc] * (1.0f - sg); qq[cc][i] = siluf_(qraw); }
.LBB0_576:
	s_lshl_b32 s0, s42, 2
	s_add_i32 s38, s0, s43
	s_ashr_i32 s0, s38, 9
	s_ashr_i32 s1, s0, 31
	s_lshl_b64 s[46:47], s[0:1], 12
	s_lshl_b32 s0, s38, 6
	s_and_b32 s0, s0, 0xfc0
	s_or_b32 s46, s46, s0
	s_lshl_b32 s0, s38, 1
	s_and_b32 s0, s0, 0x380
	v_or_b32_e32 v46, s0, v62
	v_readlane_b32 s8, v254, 29
	v_lshlrev_b32_e32 v64, 2, v46
	v_readlane_b32 s10, v254, 31
	v_readlane_b32 s11, v254, 32
	v_lshlrev_b32_e32 v96, 16, v34
	v_and_b32_e32 v97, 0xffff0000, v34
	v_lshl_add_u64 v[52:53], s[10:11], 0, v[64:65]
	v_add_co_u32_e32 v52, vcc, s50, v52
	s_nop 0
	s_nop 0
	v_addc_co_u32_e32 v53, vcc, 0, v53, vcc
	v_mul_f32_e32 v64, 0xbfb8aa3b, v96
	v_exp_f32_e32 v64, v64
	s_lshl_b32 s38, s0, 1
	v_lshlrev_b32_e32 v100, 16, v42
	v_and_b32_e32 v101, 0xffff0000, v42
	v_add_f32_e32 v64, 1.0, v64
	v_rcp_f32_e32 v104, v64
	v_mul_f32_e32 v64, 0xbfb8aa3b, v97
	v_exp_f32_e32 v64, v64
	v_lshlrev_b32_e32 v60, 16, v36
	v_and_b32_e32 v61, 0xffff0000, v36
	v_and_b32_e32 v51, 0xffff0000, v44
	v_add_f32_e32 v64, 1.0, v64
	v_rcp_f32_e32 v105, v64
	v_readlane_b32 s9, v254, 30
	v_readlane_b32 s12, v254, 33
	v_readlane_b32 s13, v254, 34
	v_pk_mul_f32 v[110:111], v[104:105], v[96:97]
	v_readlane_b32 s14, v254, 35
	v_readlane_b32 s15, v254, 36
	v_readlane_b32 s16, v254, 37
	v_readlane_b32 s17, v254, 38
	v_readlane_b32 s18, v254, 39
	v_readlane_b32 s19, v254, 40
	v_readlane_b32 s20, v254, 41
	v_readlane_b32 s21, v254, 42
	v_readlane_b32 s22, v254, 43
	v_readlane_b32 s23, v254, 44
	s_waitcnt vmcnt(24)
	v_sub_f32_e32 v46, v206, v204
	v_mul_f32_e32 v46, 0x3fb8aa3b, v46
	v_exp_f32_e32 v56, v46
	v_sub_f32_e32 v46, v207, v205
	v_mul_f32_e32 v46, 0x3fb8aa3b, v46
	v_exp_f32_e32 v57, v46
	v_lshlrev_b32_e32 v46, 16, v38
	v_mul_f32_e32 v46, 0xbfb8aa3b, v46
	v_exp_f32_e32 v46, v46
	v_pk_add_f32 v[56:57], v[56:57], 1.0 op_sel_hi:[1,0]
	v_and_b32_e32 v38, 0xffff0000, v38
	v_div_scale_f32 v64, s[0:1], v57, v57, 1.0
	v_rcp_f32_e32 v96, v64
	v_add_f32_e32 v46, 1.0, v46
	v_rcp_f32_e32 v102, v46
	v_mul_f32_e32 v34, 0xbfb8aa3b, v38
	v_fma_f32 v97, -v64, v96, 1.0
	v_fmac_f32_e32 v96, v97, v96
	v_div_scale_f32 v97, vcc, 1.0, v57, 1.0
	v_mul_f32_e32 v104, v97, v96
	v_fma_f32 v105, -v64, v104, v97
	v_fmac_f32_e32 v104, v105, v96
	v_fma_f32 v64, -v64, v104, v97
	v_div_fmas_f32 v64, v64, v96, v104
	v_div_fixup_f32 v97, v64, v57, 1.0
	v_div_scale_f32 v57, s[0:1], v56, v56, 1.0
	v_rcp_f32_e32 v64, v57
	v_exp_f32_e32 v34, v34
	v_and_b32_e32 v46, 0xffff0000, v39
	v_lshlrev_b32_e32 v38, 16, v35
	v_fma_f32 v96, -v57, v64, 1.0
	v_fmac_f32_e32 v64, v96, v64
	v_div_scale_f32 v96, vcc, 1.0, v56, 1.0
	v_mul_f32_e32 v104, v96, v64
	v_fma_f32 v105, -v57, v104, v96
	v_fmac_f32_e32 v104, v105, v64
	v_fma_f32 v57, -v57, v104, v96
	v_div_fmas_f32 v57, v57, v64, v104
	v_div_fixup_f32 v96, v57, v56, 1.0
	v_pk_add_f32 v[56:57], v[96:97], 1.0 op_sel_hi:[1,0] neg_lo:[1,0] neg_hi:[1,0]
	v_add_f32_e32 v34, 1.0, v34
	v_fma_f32 v64, v102, v56, v96
	v_cmp_gt_f32_e32 vcc, s61, v64
	v_rcp_f32_e32 v103, v34
	v_lshlrev_b32_e32 v34, 16, v39
	v_cndmask_b32_e64 v104, 0, 32, vcc
	v_ldexp_f32 v64, v64, v104
	v_log_f32_e32 v64, v64
	v_mul_f32_e32 v34, 0xbfb8aa3b, v34
	v_exp_f32_e32 v34, v34
	v_and_b32_e32 v39, 0xffff0000, v35
	v_mul_f32_e32 v104, 0x3f317217, v64
	v_fma_f32 v104, v64, s62, -v104
	v_fmac_f32_e32 v104, 0x3377d1cf, v64
	v_fmac_f32_e32 v104, 0x3f317217, v64
	v_cmp_lt_f32_e64 s[0:1], |v64|, s63
	v_add_f32_e32 v34, 1.0, v34
	v_rcp_f32_e32 v34, v34
	v_cndmask_b32_e64 v64, v64, v104, s[0:1]
	v_cndmask_b32_e32 v104, 0, v167, vcc
	v_sub_f32_e32 v104, v64, v104
	v_fma_f32 v64, v103, v57, v97
	v_cmp_gt_f32_e32 vcc, s61, v64
	v_mul_f32_e32 v35, 0xbfb8aa3b, v46
	v_exp_f32_e32 v35, v35
	v_cndmask_b32_e64 v105, 0, 32, vcc
	v_ldexp_f32 v64, v64, v105
	v_log_f32_e32 v64, v64
	v_add_f32_e32 v35, 1.0, v35
	v_rcp_f32_e32 v35, v35
	v_lshlrev_b32_e32 v46, 16, v43
	v_mul_f32_e32 v105, 0x3f317217, v64
	v_fma_f32 v105, v64, s62, -v105
	v_fmac_f32_e32 v105, 0x3377d1cf, v64
	v_fmac_f32_e32 v105, 0x3f317217, v64
	v_cmp_lt_f32_e64 s[0:1], |v64|, s63
	v_mul_f32_e32 v46, 0xbfb8aa3b, v46
	v_exp_f32_e32 v46, v46
	v_cndmask_b32_e64 v64, v64, v105, s[0:1]
	v_cndmask_b32_e32 v105, 0, v167, vcc
	v_sub_f32_e32 v105, v64, v105
	v_fma_f32 v64, v34, v56, v96
	v_cmp_gt_f32_e32 vcc, s61, v64
	v_add_f32_e32 v46, 1.0, v46
	v_rcp_f32_e32 v98, v46
	v_cndmask_b32_e64 v106, 0, 32, vcc
	v_ldexp_f32 v64, v64, v106
	v_log_f32_e32 v64, v64
	v_and_b32_e32 v43, 0xffff0000, v43
	v_mul_f32_e32 v42, 0xbfb8aa3b, v43
	v_exp_f32_e32 v42, v42
	v_mul_f32_e32 v106, 0x3f317217, v64
	v_fma_f32 v106, v64, s62, -v106
	v_fmac_f32_e32 v106, 0x3377d1cf, v64
	v_fmac_f32_e32 v106, 0x3f317217, v64
	v_cmp_lt_f32_e64 s[0:1], |v64|, s63
	v_add_f32_e32 v42, 1.0, v42
	v_rcp_f32_e32 v99, v42
	v_cndmask_b32_e64 v64, v64, v106, s[0:1]
	v_cndmask_b32_e32 v106, 0, v167, vcc
	v_sub_f32_e32 v106, v64, v106
	v_fma_f32 v64, v35, v57, v97
	v_cmp_gt_f32_e32 vcc, s61, v64
	v_lshlrev_b32_e32 v42, 16, v47
	v_mul_f32_e32 v42, 0xbfb8aa3b, v42
	v_cndmask_b32_e64 v107, 0, 32, vcc
	v_ldexp_f32 v64, v64, v107
	v_log_f32_e32 v64, v64
	v_exp_f32_e32 v42, v42
	v_and_b32_e32 v43, 0xffff0000, v47
	v_mul_f32_e32 v43, 0xbfb8aa3b, v43
	v_mul_f32_e32 v107, 0x3f317217, v64
	v_fma_f32 v107, v64, s62, -v107
	v_fmac_f32_e32 v107, 0x3377d1cf, v64
	v_fmac_f32_e32 v107, 0x3f317217, v64
	v_cmp_lt_f32_e64 s[0:1], |v64|, s63
	v_add_f32_e32 v42, 1.0, v42
	v_rcp_f32_e32 v42, v42
	v_cndmask_b32_e64 v64, v64, v107, s[0:1]
	v_cndmask_b32_e32 v107, 0, v167, vcc
	v_sub_f32_e32 v107, v64, v107
	v_fma_f32 v64, v98, v56, v96
	v_cmp_gt_f32_e32 vcc, s61, v64
	v_exp_f32_e32 v43, v43
	v_lshlrev_b32_e32 v46, 16, v50
	v_cndmask_b32_e64 v108, 0, 32, vcc
; __device__ __forceinline__ float bflo(unsigned w) { return __uint_as_float(w << 16); }
; __device__ __forceinline__ float bfhi(unsigned w) { return __uint_as_float(w & 0xffff0000u); }
; __device__ __forceinline__ float sigmoidf_(float x) { return __builtin_amdgcn_rcpf(1.0f + __expf(-x)); }
; __device__ __forceinline__ float siluf_(float x) { return x * sigmoidf_(x); }
; __device__ __forceinline__ void hgrn_passA4_sub(int u, int j, const PassARaw& R, const bf16* Z, const float* lbl, bf16* QH, bf16* OI, f32x4 (&uc)[8], float (&Lbase)[2], LAS unsigned char* lds, int tid, int wave, int lane) {
;     ...
; #pragma unroll
;         for (int i = 0; i < 8; ++i)
; #pragma unroll
;             for (int cc = 0; cc < 2; ++cc) { const float fraw = cc ? bfhi(R.f[i]) : bflo(R.f[i]), qraw = cc ? bfhi(R.q[i]) : bflo(R.q[i]);
;                 const float sg = sigmoidf_(fraw); cum[cc] += __logf(lb[cc] + omlb[cc] * sg); L[cc][i] = cum[cc]; kk[cc][i] = omlb[cc] * (1.0f - sg); qq[cc][i] = siluf_(qraw); }
	v_ldexp_f32 v64, v64, v108
	v_log_f32_e32 v64, v64
	v_add_f32_e32 v43, 1.0, v43
	v_rcp_f32_e32 v43, v43
	v_and_b32_e32 v47, 0xffff0000, v50
	v_mul_f32_e32 v108, 0x3f317217, v64
	v_fma_f32 v108, v64, s62, -v108
	v_fmac_f32_e32 v108, 0x3377d1cf, v64
	v_fmac_f32_e32 v108, 0x3f317217, v64
	v_cmp_lt_f32_e64 s[0:1], |v64|, s63
	v_lshlrev_b32_e32 v50, 16, v40
	v_mul_f32_e32 v50, 0xbfb8aa3b, v50
	v_cndmask_b32_e64 v64, v64, v108, s[0:1]
	v_cndmask_b32_e32 v108, 0, v167, vcc
	v_sub_f32_e32 v108, v64, v108
	v_fma_f32 v64, v99, v57, v97
	v_cmp_gt_f32_e32 vcc, s61, v64
	v_exp_f32_e32 v50, v50
	v_and_b32_e32 v40, 0xffff0000, v40
	v_cndmask_b32_e64 v109, 0, 32, vcc
	v_ldexp_f32 v64, v64, v109
	v_log_f32_e32 v64, v64
	v_add_f32_e32 v50, 1.0, v50
	v_rcp_f32_e32 v58, v50
	v_mul_f32_e32 v36, 0xbfb8aa3b, v40
	v_mul_f32_e32 v109, 0x3f317217, v64
	v_fma_f32 v109, v64, s62, -v109
	v_fmac_f32_e32 v109, 0x3377d1cf, v64
	v_fmac_f32_e32 v109, 0x3f317217, v64
	v_cmp_lt_f32_e64 s[0:1], |v64|, s63
	v_exp_f32_e32 v36, v36
	v_and_b32_e32 v50, 0xffff0000, v41
	v_cndmask_b32_e64 v64, v64, v109, s[0:1]
	v_cndmask_b32_e32 v109, 0, v167, vcc
	v_sub_f32_e32 v109, v64, v109
	v_fma_f32 v64, v42, v56, v96
	v_cmp_gt_f32_e32 vcc, s61, v64
	v_add_f32_e32 v36, 1.0, v36
	v_rcp_f32_e32 v59, v36
	v_cndmask_b32_e64 v112, 0, 32, vcc
	v_ldexp_f32 v64, v64, v112
	v_log_f32_e32 v64, v64
	v_lshlrev_b32_e32 v36, 16, v41
	v_mul_f32_e32 v36, 0xbfb8aa3b, v36
	v_exp_f32_e32 v36, v36
	v_mul_f32_e32 v112, 0x3f317217, v64
	v_fma_f32 v112, v64, s62, -v112
	v_fmac_f32_e32 v112, 0x3377d1cf, v64
	v_fmac_f32_e32 v112, 0x3f317217, v64
	v_cmp_lt_f32_e64 s[0:1], |v64|, s63
	v_add_f32_e32 v36, 1.0, v36
	v_rcp_f32_e32 v36, v36
	v_cndmask_b32_e64 v64, v64, v112, s[0:1]
	v_cndmask_b32_e32 v112, 0, v167, vcc
	v_sub_f32_e32 v112, v64, v112
	v_fma_f32 v64, v43, v57, v97
	v_cmp_gt_f32_e32 vcc, s61, v64
	v_lshlrev_b32_e32 v40, 16, v37
	v_and_b32_e32 v41, 0xffff0000, v37
	v_cndmask_b32_e64 v113, 0, 32, vcc
	v_ldexp_f32 v64, v64, v113
	v_log_f32_e32 v64, v64
	v_mul_f32_e32 v37, 0xbfb8aa3b, v50
	v_exp_f32_e32 v37, v37
	v_lshlrev_b32_e32 v50, 16, v49
	v_mul_f32_e32 v113, 0x3f317217, v64
	v_fma_f32 v113, v64, s62, -v113
	v_fmac_f32_e32 v113, 0x3377d1cf, v64
	v_fmac_f32_e32 v113, 0x3f317217, v64
	v_cmp_lt_f32_e64 s[0:1], |v64|, s63
	v_add_f32_e32 v37, 1.0, v37
	v_rcp_f32_e32 v37, v37
	v_cndmask_b32_e64 v64, v64, v113, s[0:1]
	v_cndmask_b32_e32 v113, 0, v167, vcc
	v_sub_f32_e32 v113, v64, v113
	v_fma_f32 v64, v58, v56, v96
	v_cmp_gt_f32_e32 vcc, s61, v64
	v_mul_f32_e32 v50, 0xbfb8aa3b, v50
	v_exp_f32_e32 v50, v50
	v_cndmask_b32_e64 v114, 0, 32, vcc
	v_ldexp_f32 v64, v64, v114
	v_log_f32_e32 v64, v64
	v_add_f32_e32 v50, 1.0, v50
	v_rcp_f32_e32 v52, v50
	v_and_b32_e32 v49, 0xffff0000, v49
	v_mul_f32_e32 v114, 0x3f317217, v64
	v_fma_f32 v114, v64, s62, -v114
	v_fmac_f32_e32 v114, 0x3377d1cf, v64
	v_fmac_f32_e32 v114, 0x3f317217, v64
	v_cmp_lt_f32_e64 s[0:1], |v64|, s63
	v_lshlrev_b32_e32 v54, 16, v48
	v_and_b32_e32 v55, 0xffff0000, v48
	v_cndmask_b32_e64 v64, v64, v114, s[0:1]
	v_cndmask_b32_e32 v114, 0, v167, vcc
	v_sub_f32_e32 v114, v64, v114
	v_fma_f32 v64, v59, v57, v97
	v_cmp_gt_f32_e32 vcc, s61, v64
	v_mul_f32_e32 v48, 0xbfb8aa3b, v49
	v_exp_f32_e32 v48, v48
	v_cndmask_b32_e64 v115, 0, 32, vcc
	v_ldexp_f32 v64, v64, v115
	v_log_f32_e32 v64, v64
	v_add_f32_e32 v48, 1.0, v48
	v_rcp_f32_e32 v53, v48
	v_lshlrev_b32_e32 v48, 16, v45
	v_mul_f32_e32 v115, 0x3f317217, v64
	v_fma_f32 v115, v64, s62, -v115
	v_fmac_f32_e32 v115, 0x3377d1cf, v64
	v_fmac_f32_e32 v115, 0x3f317217, v64
	v_cmp_lt_f32_e64 s[0:1], |v64|, s63
	v_mul_f32_e32 v48, 0xbfb8aa3b, v48
	v_exp_f32_e32 v48, v48
	v_cndmask_b32_e64 v64, v64, v115, s[0:1]
	v_cndmask_b32_e32 v115, 0, v167, vcc
	v_sub_f32_e32 v115, v64, v115
	v_fma_f32 v64, v36, v56, v96
	v_cmp_gt_f32_e32 vcc, s61, v64
	v_add_f32_e32 v48, 1.0, v48
	v_rcp_f32_e32 v48, v48
	v_cndmask_b32_e64 v116, 0, 32, vcc
	v_ldexp_f32 v64, v64, v116
	v_log_f32_e32 v64, v64
	v_and_b32_e32 v45, 0xffff0000, v45
	v_lshlrev_b32_e32 v50, 16, v44
	v_mul_f32_e32 v44, 0xbfb8aa3b, v45
	v_mul_f32_e32 v116, 0x3f317217, v64
	v_fma_f32 v116, v64, s62, -v116
	v_fmac_f32_e32 v116, 0x3377d1cf, v64
	v_fmac_f32_e32 v116, 0x3f317217, v64
	v_cmp_lt_f32_e64 s[0:1], |v64|, s63
	v_exp_f32_e32 v44, v44
	v_pk_add_f32 v[212:213], v[104:105], 0 op_sel_hi:[1,0]
	v_cndmask_b32_e64 v64, v64, v116, s[0:1]
	v_cndmask_b32_e32 v116, 0, v167, vcc
	v_sub_f32_e32 v126, v64, v116
	v_fma_f32 v64, v37, v57, v97
	v_cmp_gt_f32_e32 vcc, s61, v64
	v_add_f32_e32 v44, 1.0, v44
	v_rcp_f32_e32 v49, v44
	v_cndmask_b32_e64 v116, 0, 32, vcc
	v_ldexp_f32 v64, v64, v116
	v_log_f32_e32 v64, v64
	v_pk_add_f32 v[222:223], v[106:107], v[212:213]
	v_pk_add_f32 v[102:103], v[102:103], 1.0 op_sel_hi:[1,0] neg_lo:[1,0] neg_hi:[1,0]
	v_pk_add_f32 v[120:121], v[108:109], v[222:223]
	v_mul_f32_e32 v116, 0x3f317217, v64
	v_fma_f32 v116, v64, s62, -v116
	v_fmac_f32_e32 v116, 0x3377d1cf, v64
	v_fmac_f32_e32 v116, 0x3f317217, v64
	v_cmp_lt_f32_e64 s[0:1], |v64|, s63
	v_pk_mul_f32 v[102:103], v[102:103], v[56:57]
	v_lshl_add_u64 v[44:45], v[68:69], 0, s[38:39]
	v_cndmask_b32_e64 v64, v64, v116, s[0:1]
	v_cndmask_b32_e32 v116, 0, v167, vcc
	v_sub_f32_e32 v127, v64, v116
	v_fma_f32 v64, v52, v56, v96
	v_cmp_gt_f32_e32 vcc, s61, v64
	v_fmac_f32_e32 v96, v48, v56
	v_pk_add_f32 v[34:35], v[34:35], 1.0 op_sel_hi:[1,0] neg_lo:[1,0] neg_hi:[1,0]
	v_cndmask_b32_e64 v116, 0, 32, vcc
	v_ldexp_f32 v64, v64, v116
	v_log_f32_e32 v64, v64
	v_pk_add_f32 v[98:99], v[98:99], 1.0 op_sel_hi:[1,0] neg_lo:[1,0] neg_hi:[1,0]
	v_pk_add_f32 v[42:43], v[42:43], 1.0 op_sel_hi:[1,0] neg_lo:[1,0] neg_hi:[1,0]
; #define LAS __attribute__((address_space(3)))
; __device__ __forceinline__ float sigmoidf_(float x) { return __builtin_amdgcn_rcpf(1.0f + __expf(-x)); }
; __device__ __forceinline__ float siluf_(float x) { return x * sigmoidf_(x); }
; #define LDS_BARRIER() do { asm volatile("s_waitcnt lgkmcnt(0)" ::: "memory"); __builtin_amdgcn_s_barrier(); asm volatile("" ::: "memory"); } while (0)
; __device__ __forceinline__ void hgrn_passA4_sub(int u, int j, const PassARaw& R, const bf16* Z, const float* lbl, bf16* QH, bf16* OI, f32x4 (&uc)[8], float (&Lbase)[2], LAS unsigned char* lds, int tid, int wave, int lane) {
;     ...
;                 const float sg = sigmoidf_(fraw); cum[cc] += __logf(lb[cc] + omlb[cc] * sg); L[cc][i] = cum[cc]; kk[cc][i] = omlb[cc] * (1.0f - sg); qq[cc][i] = siluf_(qraw); }
;         LAS float* tot = (LAS float*)(lds + TOT);
;         *(LAS f32x2*)(tot + tq8 * 128 + c0) = (f32x2){cum[0], cum[1]};
;         LDS_BARRIER();
;         float pre[2] = {0.f, 0.f}, Lmid[2] = {0.f, 0.f}, Lend[2] = {0.f, 0.f};
; #pragma unroll
;         for (int g = 0; g < 8; ++g) { const f32x2 tv = *(const LAS f32x2*)(tot + g * 128 + c0);
; #pragma unroll
;             for (int cc = 0; cc < 2; ++cc) { pre[cc] += (g < tq8) ? tv[cc] : 0.f; Lmid[cc] += (g < 4) ? tv[cc] : 0.f; Lend[cc] += tv[cc]; } }
;         unsigned kh[2][4], vp[2][4];
	v_pk_mul_f32 v[98:99], v[98:99], v[56:57]
	v_mul_f32_e32 v116, 0x3f317217, v64
	v_fma_f32 v116, v64, s62, -v116
	v_fmac_f32_e32 v116, 0x3377d1cf, v64
	v_fmac_f32_e32 v116, 0x3f317217, v64
	v_cmp_lt_f32_e64 s[0:1], |v64|, s63
	v_pk_add_f32 v[58:59], v[58:59], 1.0 op_sel_hi:[1,0] neg_lo:[1,0] neg_hi:[1,0]
	v_pk_add_f32 v[36:37], v[36:37], 1.0 op_sel_hi:[1,0] neg_lo:[1,0] neg_hi:[1,0]
	v_cndmask_b32_e64 v64, v64, v116, s[0:1]
	v_cndmask_b32_e32 v116, 0, v167, vcc
	v_sub_f32_e32 v204, v64, v116
	v_fma_f32 v64, v53, v57, v97
	v_cmp_gt_f32_e32 vcc, s61, v64
	v_fmac_f32_e32 v97, v49, v57
	v_pk_mul_f32 v[58:59], v[58:59], v[56:57]
	v_cndmask_b32_e64 v116, 0, 32, vcc
	v_ldexp_f32 v64, v64, v116
	v_log_f32_e32 v64, v64
	v_pk_add_f32 v[52:53], v[52:53], 1.0 op_sel_hi:[1,0] neg_lo:[1,0] neg_hi:[1,0]
	v_pk_add_f32 v[48:49], v[48:49], 1.0 op_sel_hi:[1,0] neg_lo:[1,0] neg_hi:[1,0]
	v_pk_mul_f32 v[52:53], v[52:53], v[56:57]
	v_mul_f32_e32 v116, 0x3f317217, v64
	v_fma_f32 v116, v64, s62, -v116
	v_fmac_f32_e32 v116, 0x3377d1cf, v64
	v_fmac_f32_e32 v116, 0x3f317217, v64
	v_cmp_lt_f32_e64 s[0:1], |v64|, s63
	s_nop 1
	v_cndmask_b32_e64 v64, v64, v116, s[0:1]
	v_cndmask_b32_e32 v116, 0, v167, vcc
	v_cmp_gt_f32_e32 vcc, s61, v96
	v_sub_f32_e32 v205, v64, v116
	v_pk_add_f32 v[116:117], v[112:113], v[120:121]
	v_cndmask_b32_e64 v64, 0, 32, vcc
	v_ldexp_f32 v64, v96, v64
	v_log_f32_e32 v64, v64
	v_pk_add_f32 v[114:115], v[114:115], v[116:117]
	v_mul_f32_e32 v96, 0x3f317217, v64
	v_fma_f32 v96, v64, s62, -v96
	v_fmac_f32_e32 v96, 0x3377d1cf, v64
	v_fmac_f32_e32 v96, 0x3f317217, v64
	v_cmp_lt_f32_e64 s[0:1], |v64|, s63
	v_pk_add_f32 v[112:113], v[126:127], v[114:115]
	s_nop 0
	v_cndmask_b32_e64 v64, v64, v96, s[0:1]
	v_cndmask_b32_e32 v96, 0, v167, vcc
	v_cmp_gt_f32_e32 vcc, s61, v97
	v_sub_f32_e32 v96, v64, v96
	v_pk_add_f32 v[108:109], v[204:205], v[112:113]
	v_cndmask_b32_e64 v64, 0, 32, vcc
	v_ldexp_f32 v64, v97, v64
	v_log_f32_e32 v64, v64
	s_nop 0
	v_mul_f32_e32 v97, 0x3f317217, v64
	v_fma_f32 v97, v64, s62, -v97
	v_fmac_f32_e32 v97, 0x3377d1cf, v64
	v_fmac_f32_e32 v97, 0x3f317217, v64
	v_cmp_lt_f32_e64 s[0:1], |v64|, s63
	s_nop 1
	v_cndmask_b32_e64 v64, v64, v97, s[0:1]
	v_cndmask_b32_e32 v97, 0, v167, vcc
	v_sub_f32_e32 v97, v64, v97
	v_pk_add_f32 v[104:105], v[96:97], v[108:109]
	ds_write_b64 v129, v[104:105]
	s_waitcnt lgkmcnt(0)
	s_barrier
	ds_read2st64_b64 v[204:207], v128 offset1:1
	ds_read2st64_b64 v[208:211], v128 offset0:2 offset1:3
	ds_read2st64_b64 v[232:235], v128 offset0:4 offset1:5
	ds_read2st64_b64 v[236:239], v128 offset0:6 offset1:7
	s_waitcnt lgkmcnt(3)
	v_pk_add_f32 v[96:97], v[204:205], 0 op_sel_hi:[1,0]
	v_cndmask_b32_e64 v64, 0, v206, s[6:7]
	v_cndmask_b32_e64 v204, v96, 0, s[4:5]
	v_cndmask_b32_e64 v106, 0, v207, s[6:7]
	s_waitcnt lgkmcnt(2)
	v_cndmask_b32_e64 v107, 0, v208, s[66:67]
	v_cndmask_b32_e64 v205, v97, 0, s[4:5]
	v_add_f32_e32 v64, v204, v64
	v_cndmask_b32_e64 v118, 0, v209, s[66:67]
	v_cndmask_b32_e64 v123, 0, v210, s[68:69]
	v_add_f32_e32 v106, v205, v106
	v_add_f32_e32 v64, v64, v107
	v_cndmask_b32_e64 v124, 0, v211, s[68:69]
	s_waitcnt lgkmcnt(1)
	v_cndmask_b32_e64 v126, 0, v232, s[72:73]
	v_add_f32_e32 v106, v106, v118
	v_add_f32_e32 v64, v64, v123
	v_cndmask_b32_e64 v127, 0, v233, s[72:73]
	v_cndmask_b32_e64 v231, 0, v234, s[74:75]
	v_add_f32_e32 v118, v106, v124
	v_add_f32_e32 v64, v64, v126
	v_cndmask_b32_e64 v240, 0, v235, s[74:75]
	s_waitcnt lgkmcnt(0)
	v_cndmask_b32_e64 v241, 0, v236, s[52:53]
	v_add_f32_e32 v118, v118, v127
	v_add_f32_e32 v64, v64, v231
	v_cndmask_b32_e64 v242, 0, v237, s[52:53]
	v_cndmask_b32_e64 v243, 0, v238, s[54:55]
	v_pk_add_f32 v[96:97], v[96:97], v[206:207]
	v_add_f32_e32 v118, v118, v240
	v_add_f32_e32 v64, v64, v241
	v_cndmask_b32_e64 v244, 0, v239, s[54:55]
	v_pk_add_f32 v[96:97], v[96:97], v[208:209]
	v_add_f32_e32 v118, v118, v242
	v_add_f32_e32 v204, v64, v243
	v_pk_add_f32 v[106:107], v[96:97], v[210:211]
	v_add_f32_e32 v64, v118, v244
	v_add_f32_e32 v118, v212, v204
	v_sub_f32_e32 v123, v118, v106
	v_min_f32_e32 v123, 0x42a00000, v123
	v_mul_f32_e32 v123, 0x3fb8aa3b, v123
	v_exp_f32_e32 v126, v123
	v_sub_f32_e32 v123, v106, v118
	v_min_f32_e32 v123, 0x42a00000, v123
	v_mul_f32_e32 v123, 0x3fb8aa3b, v123
	v_exp_f32_e32 v206, v123
	v_mul_f32_e32 v123, 0x3fb8aa3b, v118
	v_exp_f32_e32 v208, v123
	v_add_f32_e32 v123, v94, v118
	v_mul_f32_e32 v123, 0x3fb8aa3b, v123
	v_exp_f32_e32 v210, v123
	v_add_f32_e32 v123, v213, v64
	v_sub_f32_e32 v124, v123, v107
	v_min_f32_e32 v124, 0x42a00000, v124
	v_mul_f32_e32 v124, 0x3fb8aa3b, v124
	v_exp_f32_e32 v127, v124
	v_sub_f32_e32 v124, v107, v123
	v_min_f32_e32 v124, 0x42a00000, v124
	v_mul_f32_e32 v124, 0x3fb8aa3b, v124
	v_exp_f32_e32 v207, v124
	v_mul_f32_e32 v124, 0x3fb8aa3b, v123
	v_exp_f32_e32 v209, v124
	v_add_f32_e32 v124, v95, v123
	v_mul_f32_e32 v124, 0x3fb8aa3b, v124
	v_exp_f32_e32 v211, v124
	v_pk_mul_f32 v[126:127], v[110:111], v[126:127]
	v_pk_mul_f32 v[206:207], v[102:103], v[206:207]
	v_pk_mul_f32 v[208:209], v[110:111], v[208:209]
	v_cvt_pk_bf16_f32 v124, v126, v127
	v_add_u32_e32 v126, v130, v132
	v_cvt_pk_bf16_f32 v127, v206, v207
	v_pk_add_f32 v[96:97], v[232:233], v[106:107]
	v_pk_mul_f32 v[110:111], v[110:111], v[210:211]
	ds_write2st64_b32 v126, v124, v127 offset0:16 offset1:84
	v_cvt_pk_bf16_f32 v124, v208, v209
	v_add_u32_e32 v126, v131, v132
	v_mul_f32_e32 v127, 0xbfb8aa3b, v38
	v_pk_add_f32 v[96:97], v[234:235], v[96:97]
	ds_write_b32 v126, v124
	v_cvt_pk_bf16_f32 v124, v110, v111
	v_lshl_add_u64 v[110:111], s[46:47], 0, v[66:67]
	v_exp_f32_e32 v127, v127
	v_pk_add_f32 v[96:97], v[236:237], v[96:97]
; #define LAS __attribute__((address_space(3)))
; __device__ __forceinline__ unsigned pk2(float lo, float hi) { f32x2 v = {lo, hi}; bf16x2_t b = __builtin_convertvector(v, bf16x2_t); return __builtin_bit_cast(unsigned, b); }
; __device__ __forceinline__ unsigned short f2bf(float f) { return (unsigned short)(pk2(f, 0.f) & 0xffffu); }
; __device__ __forceinline__ void hgrn_passA4_sub(int u, int j, const PassARaw& R, const bf16* Z, const float* lbl, bf16* QH, bf16* OI, f32x4 (&uc)[8], float (&Lbase)[2], LAS unsigned char* lds, int tid, int wave, int lane) {
;     ...
;         for (int i = 0; i < 8; ++i) { const int t = tq8 * 8 + i; float qt[2], kt[2], qlv[2], qhv[2]; unsigned short khv[2];
; #pragma unroll
;             for (int cc = 0; cc < 2; ++cc) { const float Lt = pre[cc] + L[cc][i];
;                 qt[cc] = qq[cc][i] * __expf(fminf(Lt - Lmid[cc], 80.f)); kt[cc] = kk[cc][i] * __expf(fminf(Lmid[cc] - Lt, 80.f));
;                 qlv[cc] = qq[cc][i] * __expf(Lt); qhv[cc] = qq[cc][i] * __expf(Lbase[cc] + Lt); khv[cc] = f2bf(kk[cc][i] * __expf(Lend[cc] - Lt)); }
;             *(LAS unsigned*)(lds + QT + t * 272 + c0 * 2) = pk2(qt[0], qt[1]); *(LAS unsigned*)(lds + KT + t * 272 + c0 * 2) = pk2(kt[0], kt[1]);
;             *(LAS unsigned*)(lds + QL + t * 272 + c0 * 2) = pk2(qlv[0], qlv[1]);
;             *(unsigned*)(QH + (r0 + t) * 1024 + h * 128 + c0) = pk2(qhv[0], qhv[1]);
	v_lshlrev_b64 v[110:111], 11, v[110:111]
	v_pk_add_f32 v[96:97], v[238:239], v[96:97]
	v_lshl_add_u64 v[110:111], v[44:45], 0, v[110:111]
	v_add_f32_e32 v213, v222, v204
	global_store_dword v[110:111], v124, off
	v_sub_f32_e32 v110, v97, v123
	v_sub_f32_e32 v123, v106, v213
	v_min_f32_e32 v123, 0x42a00000, v123
	v_add_f32_e32 v127, 1.0, v127
	v_mul_f32_e32 v123, 0x3fb8aa3b, v123
	v_rcp_f32_e32 v210, v127
	v_mul_f32_e32 v127, 0xbfb8aa3b, v39
	v_exp_f32_e32 v126, v123
	v_mul_f32_e32 v123, 0x3fb8aa3b, v213
	v_exp_f32_e32 v127, v127
	v_exp_f32_e32 v206, v123
	v_add_f32_e32 v123, v94, v213
	v_mul_f32_e32 v123, 0x3fb8aa3b, v123
	v_add_f32_e32 v124, v223, v64
	v_and_b32_e32 v111, 0xffff, v122
	v_lshrrev_b32_e32 v212, 16, v122
	v_sub_f32_e32 v122, v213, v106
	v_exp_f32_e32 v208, v123
	v_sub_f32_e32 v123, v124, v107
	v_min_f32_e32 v122, 0x42a00000, v122
	v_min_f32_e32 v123, 0x42a00000, v123
	v_add_f32_e32 v127, 1.0, v127
	v_mul_f32_e32 v122, 0x3fb8aa3b, v122
	v_mul_f32_e32 v123, 0x3fb8aa3b, v123
	v_rcp_f32_e32 v211, v127
	v_exp_f32_e32 v122, v122
	v_exp_f32_e32 v123, v123
	v_add_f32_e32 v205, v95, v124
	v_pk_mul_f32 v[38:39], v[210:211], v[38:39]
	v_mul_f32_e32 v205, 0x3fb8aa3b, v205
	v_pk_mul_f32 v[210:211], v[38:39], v[122:123]
	v_sub_f32_e32 v122, v107, v124
	v_min_f32_e32 v122, 0x42a00000, v122
	v_mul_f32_e32 v122, 0x3fb8aa3b, v122
	v_exp_f32_e32 v127, v122
	v_pk_mul_f32 v[122:123], v[34:35], v[56:57]
	v_exp_f32_e32 v209, v205
	v_add_u32_e32 v205, v130, v133
	v_pk_mul_f32 v[34:35], v[122:123], v[126:127]
	v_mul_f32_e32 v126, 0x3fb8aa3b, v124
	v_exp_f32_e32 v207, v126
	v_cvt_pk_bf16_f32 v34, v34, v35
	ds_write_b32 v205, v34 offset:21504
	v_mul_f32_e32 v110, 0x3fb8aa3b, v110
	v_pk_mul_f32 v[126:127], v[38:39], v[206:207]
	v_cvt_pk_bf16_f32 v206, v210, v211
	ds_write_b32 v205, v206 offset:4096
	v_cvt_pk_bf16_f32 v34, v126, v127
	v_add_u32_e32 v206, v131, v133
	ds_write_b32 v206, v34
	v_lshl_add_u64 v[34:35], s[46:47], 0, v[70:71]
	v_pk_mul_f32 v[38:39], v[38:39], v[208:209]
	v_lshlrev_b64 v[34:35], 11, v[34:35]
	v_cvt_pk_bf16_f32 v38, v38, v39
	v_lshl_add_u64 v[34:35], v[44:45], 0, v[34:35]
	global_store_dword v[34:35], v38, off
	v_add_f32_e32 v35, v120, v204
	v_sub_f32_e32 v39, v35, v106
	v_min_f32_e32 v39, 0x42a00000, v39
	v_mul_f32_e32 v39, 0x3fb8aa3b, v39
	v_exp_f32_e32 v120, v39
	v_sub_f32_e32 v39, v106, v35
	v_min_f32_e32 v39, 0x42a00000, v39
	v_sub_f32_e32 v34, v97, v124
	v_mul_f32_e32 v39, 0x3fb8aa3b, v39
	v_mul_f32_e32 v34, 0x3fb8aa3b, v34
	v_exp_f32_e32 v208, v39
	v_mul_f32_e32 v39, 0x3fb8aa3b, v35
	v_exp_f32_e32 v124, v34
	v_sub_f32_e32 v34, v96, v213
	v_exp_f32_e32 v210, v39
	v_add_f32_e32 v39, v94, v35
	v_mul_f32_e32 v34, 0x3fb8aa3b, v34
	v_mul_f32_e32 v39, 0x3fb8aa3b, v39
	v_exp_f32_e32 v126, v34
	v_and_or_b32 v34, v119, s60, v212
	v_exp_f32_e32 v212, v39
	v_add_f32_e32 v39, v121, v64
	v_lshl_or_b32 v38, v119, 16, v111
	v_sub_f32_e32 v111, v39, v107
	v_min_f32_e32 v111, 0x42a00000, v111
	v_mul_f32_e32 v111, 0x3fb8aa3b, v111
	v_exp_f32_e32 v121, v111
	v_mul_f32_e32 v111, 0xbfb8aa3b, v100
	v_exp_f32_e32 v111, v111
	v_sub_f32_e32 v35, v96, v35
	v_mul_f32_e32 v35, 0x3fb8aa3b, v35
	v_and_b32_e32 v207, 0xffff, v125
	v_add_f32_e32 v111, 1.0, v111
	v_rcp_f32_e32 v222, v111
	v_mul_f32_e32 v111, 0xbfb8aa3b, v101
	v_exp_f32_e32 v111, v111
	v_exp_f32_e32 v119, v35
	v_lshrrev_b32_e32 v35, 16, v125
	v_add_f32_e32 v125, v117, v64
	v_add_f32_e32 v111, 1.0, v111
	v_rcp_f32_e32 v223, v111
	v_sub_f32_e32 v111, v107, v39
	v_min_f32_e32 v111, 0x42a00000, v111
	v_mul_f32_e32 v111, 0x3fb8aa3b, v111
	v_exp_f32_e32 v209, v111
	v_mul_f32_e32 v111, 0x3fb8aa3b, v39
	v_mul_f32_e32 v117, 0xbfb8aa3b, v46
	v_exp_f32_e32 v211, v111
	v_add_f32_e32 v111, v95, v39
	v_exp_f32_e32 v117, v117
	v_pk_mul_f32 v[100:101], v[222:223], v[100:101]
	v_mul_f32_e32 v111, 0x3fb8aa3b, v111
	v_pk_mul_f32 v[120:121], v[100:101], v[120:121]
	v_exp_f32_e32 v213, v111
	v_pk_mul_f32 v[208:209], v[98:99], v[208:209]
	v_cvt_pk_bf16_f32 v111, v120, v121
	v_pk_mul_f32 v[210:211], v[100:101], v[210:211]
	ds_write_b32 v205, v111 offset:4368
	v_cvt_pk_bf16_f32 v111, v208, v209
	v_add_f32_e32 v117, 1.0, v117
	ds_write_b32 v205, v111 offset:21776
	v_cvt_pk_bf16_f32 v111, v210, v211
	v_rcp_f32_e32 v210, v117
	v_mul_f32_e32 v117, 0xbfb8aa3b, v47
	v_pk_mul_f32 v[100:101], v[100:101], v[212:213]
	v_exp_f32_e32 v117, v117
	ds_write_b32 v206, v111 offset:272
	v_cvt_pk_bf16_f32 v111, v100, v101
	v_lshl_add_u64 v[100:101], s[46:47], 0, v[72:73]
	v_lshlrev_b64 v[100:101], 11, v[100:101]
	v_sub_f32_e32 v39, v97, v39
	v_lshl_add_u64 v[100:101], v[44:45], 0, v[100:101]
	v_mul_f32_e32 v39, 0x3fb8aa3b, v39
	global_store_dword v[100:101], v111, off
	v_exp_f32_e32 v111, v39
	v_add_f32_e32 v39, v116, v204
	v_add_f32_e32 v117, 1.0, v117
	v_sub_f32_e32 v101, v106, v39
	v_rcp_f32_e32 v211, v117
	v_sub_f32_e32 v117, v107, v125
	v_min_f32_e32 v101, 0x42a00000, v101
	v_min_f32_e32 v117, 0x42a00000, v117
	v_mul_f32_e32 v101, 0x3fb8aa3b, v101
	v_mul_f32_e32 v117, 0x3fb8aa3b, v117
	v_exp_f32_e32 v116, v101
	v_exp_f32_e32 v117, v117
	v_mul_f32_e32 v101, 0x3fb8aa3b, v39
	v_exp_f32_e32 v120, v101
	v_add_f32_e32 v101, v94, v39
	v_pk_mul_f32 v[46:47], v[210:211], v[46:47]
	v_pk_mul_f32 v[210:211], v[42:43], v[56:57]
	v_mul_f32_e32 v101, 0x3fb8aa3b, v101
	v_pk_mul_f32 v[42:43], v[210:211], v[116:117]
	v_mul_f32_e32 v116, 0x3fb8aa3b, v125
	v_sub_f32_e32 v100, v39, v106
	v_exp_f32_e32 v208, v101
	v_sub_f32_e32 v101, v125, v107
	v_exp_f32_e32 v121, v116
	v_min_f32_e32 v100, 0x42a00000, v100
	v_min_f32_e32 v101, 0x42a00000, v101
	v_mul_f32_e32 v100, 0x3fb8aa3b, v100
	v_mul_f32_e32 v101, 0x3fb8aa3b, v101
	v_exp_f32_e32 v100, v100
; #define LAS __attribute__((address_space(3)))
; __device__ __forceinline__ unsigned pk2(float lo, float hi) { f32x2 v = {lo, hi}; bf16x2_t b = __builtin_convertvector(v, bf16x2_t); return __builtin_bit_cast(unsigned, b); }
; __device__ __forceinline__ unsigned short f2bf(float f) { return (unsigned short)(pk2(f, 0.f) & 0xffffu); }
; __device__ __forceinline__ void hgrn_passA4_sub(int u, int j, const PassARaw& R, const bf16* Z, const float* lbl, bf16* QH, bf16* OI, f32x4 (&uc)[8], float (&Lbase)[2], LAS unsigned char* lds, int tid, int wave, int lane) {
;     ...
;         for (int i = 0; i < 8; ++i) { const int t = tq8 * 8 + i; float qt[2], kt[2], qlv[2], qhv[2]; unsigned short khv[2];
; #pragma unroll
;             for (int cc = 0; cc < 2; ++cc) { const float Lt = pre[cc] + L[cc][i];
;                 qt[cc] = qq[cc][i] * __expf(fminf(Lt - Lmid[cc], 80.f)); kt[cc] = kk[cc][i] * __expf(fminf(Lmid[cc] - Lt, 80.f));
;                 qlv[cc] = qq[cc][i] * __expf(Lt); qhv[cc] = qq[cc][i] * __expf(Lbase[cc] + Lt); khv[cc] = f2bf(kk[cc][i] * __expf(Lend[cc] - Lt)); }
;             *(LAS unsigned*)(lds + QT + t * 272 + c0 * 2) = pk2(qt[0], qt[1]); *(LAS unsigned*)(lds + KT + t * 272 + c0 * 2) = pk2(kt[0], kt[1]);
;             *(LAS unsigned*)(lds + QL + t * 272 + c0 * 2) = pk2(qlv[0], qlv[1]);
;             *(unsigned*)(QH + (r0 + t) * 1024 + h * 128 + c0) = pk2(qhv[0], qhv[1]);
;             const unsigned v0 = R.v[i] & 0xffffu, v1 = R.v[i] >> 16;
;             if (i & 1) { kh[0][i >> 1] |= (unsigned)khv[0] << 16; kh[1][i >> 1] |= (unsigned)khv[1] << 16; vp[0][i >> 1] |= v0 << 16; vp[1][i >> 1] |= v1 << 16; }
;             else { kh[0][i >> 1] = khv[0]; kh[1][i >> 1] = khv[1]; vp[0][i >> 1] = v0; vp[1][i >> 1] = v1; } }
	v_exp_f32_e32 v101, v101
	v_pk_mul_f32 v[116:117], v[46:47], v[120:121]
	v_add_f32_e32 v120, v95, v125
	v_mul_f32_e32 v120, 0x3fb8aa3b, v120
	v_exp_f32_e32 v209, v120
	v_pk_mul_f32 v[100:101], v[46:47], v[100:101]
	v_cvt_pk_bf16_f32 v42, v42, v43
	v_cvt_pk_bf16_f32 v100, v100, v101
	ds_write_b32 v205, v42 offset:22048
	v_cvt_pk_bf16_f32 v42, v116, v117
	v_mul_f32_e32 v101, 0xbfb8aa3b, v60
	v_exp_f32_e32 v110, v110
	ds_write_b32 v205, v100 offset:4640
	ds_write_b32 v206, v42 offset:544
	v_lshl_add_u64 v[42:43], s[46:47], 0, v[74:75]
	v_exp_f32_e32 v101, v101
	v_pk_mul_f32 v[46:47], v[46:47], v[208:209]
	v_lshlrev_b64 v[42:43], 11, v[42:43]
	v_cvt_pk_bf16_f32 v46, v46, v47
	v_lshl_add_u64 v[42:43], v[44:45], 0, v[42:43]
	global_store_dword v[42:43], v46, off
	v_mov_b32_e32 v43, v98
	v_mov_b32_e32 v98, v103
	v_add_f32_e32 v116, v114, v204
	v_pk_mul_f32 v[46:47], v[98:99], v[110:111]
	v_sub_f32_e32 v99, v106, v116
	v_add_f32_e32 v101, 1.0, v101
	v_min_f32_e32 v99, 0x42a00000, v99
	v_rcp_f32_e32 v114, v101
	v_mul_f32_e32 v101, 0xbfb8aa3b, v61
	v_sub_f32_e32 v42, v97, v125
	v_mul_f32_e32 v99, 0x3fb8aa3b, v99
	v_exp_f32_e32 v101, v101
	v_mul_f32_e32 v42, 0x3fb8aa3b, v42
	v_exp_f32_e32 v100, v99
	v_mul_f32_e32 v99, 0x3fb8aa3b, v116
	v_exp_f32_e32 v125, v42
	v_mov_b32_e32 v42, v102
	v_exp_f32_e32 v102, v99
	v_add_f32_e32 v99, v94, v116
	v_mul_f32_e32 v99, 0x3fb8aa3b, v99
	v_add_f32_e32 v117, v115, v64
	v_sub_f32_e32 v98, v116, v106
	v_exp_f32_e32 v110, v99
	v_sub_f32_e32 v99, v117, v107
	v_add_f32_e32 v101, 1.0, v101
	v_min_f32_e32 v98, 0x42a00000, v98
	v_min_f32_e32 v99, 0x42a00000, v99
	v_rcp_f32_e32 v115, v101
	v_sub_f32_e32 v101, v107, v117
	v_mul_f32_e32 v98, 0x3fb8aa3b, v98
	v_mul_f32_e32 v99, 0x3fb8aa3b, v99
	v_min_f32_e32 v101, 0x42a00000, v101
	v_exp_f32_e32 v98, v98
	v_exp_f32_e32 v99, v99
	v_mul_f32_e32 v101, 0x3fb8aa3b, v101
	v_exp_f32_e32 v101, v101
	v_mul_f32_e32 v103, 0x3fb8aa3b, v117
	v_add_f32_e32 v111, v95, v117
	v_exp_f32_e32 v103, v103
	v_mul_f32_e32 v111, 0x3fb8aa3b, v111
	v_pk_mul_f32 v[60:61], v[114:115], v[60:61]
	v_exp_f32_e32 v111, v111
	v_pk_mul_f32 v[98:99], v[60:61], v[98:99]
	v_pk_mul_f32 v[100:101], v[58:59], v[100:101]
	v_cvt_pk_bf16_f32 v98, v98, v99
	v_pk_mul_f32 v[102:103], v[60:61], v[102:103]
	ds_write_b32 v205, v98 offset:4912
	v_cvt_pk_bf16_f32 v98, v100, v101
	v_pk_mul_f32 v[60:61], v[60:61], v[110:111]
	ds_write_b32 v205, v98 offset:22320
	v_cvt_pk_bf16_f32 v98, v102, v103
	ds_write_b32 v206, v98 offset:816
	v_cvt_pk_bf16_f32 v98, v60, v61
	v_lshl_add_u64 v[60:61], s[46:47], 0, v[76:77]
	v_lshlrev_b64 v[60:61], 11, v[60:61]
	v_lshl_add_u64 v[60:61], v[44:45], 0, v[60:61]
	v_mul_f32_e32 v103, 0xbfb8aa3b, v40
	global_store_dword v[60:61], v98, off
	v_sub_f32_e32 v60, v97, v117
	v_exp_f32_e32 v103, v103
	v_mul_f32_e32 v60, 0x3fb8aa3b, v60
	v_exp_f32_e32 v98, v60
	v_sub_f32_e32 v60, v96, v116
	v_add_f32_e32 v116, v112, v204
	v_sub_f32_e32 v101, v106, v116
	v_min_f32_e32 v101, 0x42a00000, v101
	v_add_f32_e32 v103, 1.0, v103
	v_mul_f32_e32 v101, 0x3fb8aa3b, v101
	v_rcp_f32_e32 v114, v103
	v_mul_f32_e32 v103, 0xbfb8aa3b, v41
	v_exp_f32_e32 v102, v101
	v_mul_f32_e32 v101, 0x3fb8aa3b, v116
	v_exp_f32_e32 v103, v103
	v_exp_f32_e32 v110, v101
	v_add_f32_e32 v101, v94, v116
	v_mul_f32_e32 v101, 0x3fb8aa3b, v101
	v_add_f32_e32 v117, v64, v113
	v_sub_f32_e32 v100, v116, v106
	v_exp_f32_e32 v112, v101
	v_sub_f32_e32 v101, v117, v107
	v_min_f32_e32 v100, 0x42a00000, v100
	v_min_f32_e32 v101, 0x42a00000, v101
	v_add_f32_e32 v103, 1.0, v103
	v_mul_f32_e32 v100, 0x3fb8aa3b, v100
	v_mul_f32_e32 v101, 0x3fb8aa3b, v101
	v_rcp_f32_e32 v115, v103
	v_exp_f32_e32 v100, v100
	v_exp_f32_e32 v101, v101
	v_and_b32_e32 v61, 0xffff, v202
	v_pk_mul_f32 v[40:41], v[114:115], v[40:41]
	v_sub_f32_e32 v118, v96, v118
	v_pk_mul_f32 v[114:115], v[40:41], v[100:101]
	v_sub_f32_e32 v100, v107, v117
	v_min_f32_e32 v100, 0x42a00000, v100
	v_mul_f32_e32 v100, 0x3fb8aa3b, v100
	v_exp_f32_e32 v103, v100
	v_pk_mul_f32 v[100:101], v[36:37], v[56:57]
	v_mul_f32_e32 v118, 0x3fb8aa3b, v118
	v_exp_f32_e32 v118, v118
	v_pk_mul_f32 v[36:37], v[100:101], v[102:103]
	v_mul_f32_e32 v102, 0x3fb8aa3b, v117
	v_exp_f32_e32 v111, v102
	v_cvt_pk_bf16_f32 v36, v36, v37
	ds_write_b32 v205, v36 offset:22592
	v_pk_mul_f32 v[42:43], v[42:43], v[118:119]
	v_pk_mul_f32 v[102:103], v[40:41], v[110:111]
	v_add_f32_e32 v110, v95, v117
	v_mul_f32_e32 v110, 0x3fb8aa3b, v110
	v_exp_f32_e32 v113, v110
	v_cvt_pk_bf16_f32 v110, v114, v115
	v_cvt_pk_bf16_f32 v36, v102, v103
	ds_write_b32 v205, v110 offset:5184
	ds_write_b32 v206, v36 offset:1088
	v_lshl_add_u64 v[36:37], s[46:47], 0, v[78:79]
	v_pk_mul_f32 v[40:41], v[40:41], v[112:113]
	v_lshlrev_b64 v[36:37], 11, v[36:37]
	v_cvt_pk_bf16_f32 v40, v40, v41
	v_lshl_add_u64 v[36:37], v[44:45], 0, v[36:37]
	global_store_dword v[36:37], v40, off
	v_add_f32_e32 v37, v108, v204
	v_sub_f32_e32 v41, v37, v106
	v_min_f32_e32 v41, 0x42a00000, v41
	v_mul_f32_e32 v41, 0x3fb8aa3b, v41
	v_exp_f32_e32 v108, v41
	v_sub_f32_e32 v41, v106, v37
	v_min_f32_e32 v41, 0x42a00000, v41
	v_mul_f32_e32 v41, 0x3fb8aa3b, v41
	v_exp_f32_e32 v112, v41
	v_mul_f32_e32 v41, 0x3fb8aa3b, v37
	v_sub_f32_e32 v36, v97, v117
	v_exp_f32_e32 v114, v41
	v_add_f32_e32 v41, v94, v37
	v_mul_f32_e32 v36, 0x3fb8aa3b, v36
	v_mul_f32_e32 v41, 0x3fb8aa3b, v41
	v_exp_f32_e32 v110, v36
	v_sub_f32_e32 v36, v96, v116
	v_exp_f32_e32 v116, v41
	v_add_f32_e32 v41, v64, v109
	v_lshl_or_b32 v40, v201, 16, v61
	v_sub_f32_e32 v61, v41, v107
	v_min_f32_e32 v61, 0x42a00000, v61
	v_mul_f32_e32 v61, 0x3fb8aa3b, v61
	v_exp_f32_e32 v109, v61
	v_mul_f32_e32 v61, 0xbfb8aa3b, v54
	v_exp_f32_e32 v61, v61
; #define LAS __attribute__((address_space(3)))
; __device__ __forceinline__ unsigned pk2(float lo, float hi) { f32x2 v = {lo, hi}; bf16x2_t b = __builtin_convertvector(v, bf16x2_t); return __builtin_bit_cast(unsigned, b); }
; __device__ __forceinline__ unsigned short f2bf(float f) { return (unsigned short)(pk2(f, 0.f) & 0xffffu); }
; __device__ __forceinline__ void hgrn_passA4_sub(int u, int j, const PassARaw& R, const bf16* Z, const float* lbl, bf16* QH, bf16* OI, f32x4 (&uc)[8], float (&Lbase)[2], LAS unsigned char* lds, int tid, int wave, int lane) {
;     ...
;         for (int i = 0; i < 8; ++i) { const int t = tq8 * 8 + i; float qt[2], kt[2], qlv[2], qhv[2]; unsigned short khv[2];
; #pragma unroll
;             for (int cc = 0; cc < 2; ++cc) { const float Lt = pre[cc] + L[cc][i];
;                 qt[cc] = qq[cc][i] * __expf(fminf(Lt - Lmid[cc], 80.f)); kt[cc] = kk[cc][i] * __expf(fminf(Lmid[cc] - Lt, 80.f));
;                 qlv[cc] = qq[cc][i] * __expf(Lt); qhv[cc] = qq[cc][i] * __expf(Lbase[cc] + Lt); khv[cc] = f2bf(kk[cc][i] * __expf(Lend[cc] - Lt)); }
;             *(LAS unsigned*)(lds + QT + t * 272 + c0 * 2) = pk2(qt[0], qt[1]); *(LAS unsigned*)(lds + KT + t * 272 + c0 * 2) = pk2(kt[0], kt[1]);
;             *(LAS unsigned*)(lds + QL + t * 272 + c0 * 2) = pk2(qlv[0], qlv[1]);
;             *(unsigned*)(QH + (r0 + t) * 1024 + h * 128 + c0) = pk2(qhv[0], qhv[1]);
;             const unsigned v0 = R.v[i] & 0xffffu, v1 = R.v[i] >> 16;
;             if (i & 1) { kh[0][i >> 1] |= (unsigned)khv[0] << 16; kh[1][i >> 1] |= (unsigned)khv[1] << 16; vp[0][i >> 1] |= v0 << 16; vp[1][i >> 1] |= v1 << 16; }
;             else { kh[0][i >> 1] = khv[0]; kh[1][i >> 1] = khv[1]; vp[0][i >> 1] = v0; vp[1][i >> 1] = v1; } }
; #pragma unroll
;         for (int cc = 0; cc < 2; ++cc) { *(LAS u32x4*)(lds + KH + (c0 + cc) * 144 + tq8 * 16) = (u32x4){kh[cc][0], kh[cc][1], kh[cc][2], kh[cc][3]};
;             *(LAS u32x4*)(lds + VT + (c0 + cc) * 144 + tq8 * 16) = (u32x4){vp[cc][0], vp[cc][1], vp[cc][2], vp[cc][3]}; }
;         if (tq8 == 0) *(LAS f32x2*)(lds + DCL + c0 * 4) = (f32x2){__expf(Lend[0]), __expf(Lend[1])};
	v_lshrrev_b32_e32 v99, 16, v202
	v_mul_f32_e32 v36, 0x3fb8aa3b, v36
	v_exp_f32_e32 v102, v36
	v_add_f32_e32 v61, 1.0, v61
	v_rcp_f32_e32 v118, v61
	v_mul_f32_e32 v61, 0xbfb8aa3b, v55
	v_exp_f32_e32 v61, v61
	v_and_or_b32 v36, v201, s60, v99
	v_add_f32_e32 v64, v64, v105
	v_pk_mul_f32 v[56:57], v[48:49], v[56:57]
	v_add_f32_e32 v61, 1.0, v61
	v_rcp_f32_e32 v119, v61
	v_sub_f32_e32 v61, v107, v41
	v_min_f32_e32 v61, 0x42a00000, v61
	v_mul_f32_e32 v61, 0x3fb8aa3b, v61
	v_exp_f32_e32 v113, v61
	v_mul_f32_e32 v61, 0x3fb8aa3b, v41
	v_exp_f32_e32 v115, v61
	v_add_f32_e32 v61, v95, v41
	v_mul_f32_e32 v61, 0x3fb8aa3b, v61
	v_pk_mul_f32 v[54:55], v[118:119], v[54:55]
	v_exp_f32_e32 v117, v61
	v_pk_mul_f32 v[108:109], v[54:55], v[108:109]
	v_pk_mul_f32 v[112:113], v[52:53], v[112:113]
	v_cvt_pk_bf16_f32 v61, v108, v109
	v_pk_mul_f32 v[114:115], v[54:55], v[114:115]
	ds_write_b32 v205, v61 offset:5456
	v_cvt_pk_bf16_f32 v61, v112, v113
	v_sub_f32_e32 v41, v97, v41
	v_pk_mul_f32 v[54:55], v[54:55], v[116:117]
	ds_write_b32 v205, v61 offset:22864
	v_cvt_pk_bf16_f32 v61, v114, v115
	v_mul_f32_e32 v41, 0x3fb8aa3b, v41
	v_add_f32_e32 v114, v204, v104
	ds_write_b32 v206, v61 offset:1360
	v_cvt_pk_bf16_f32 v61, v54, v55
	v_lshl_add_u64 v[54:55], s[46:47], 0, v[80:81]
	v_exp_f32_e32 v99, v41
	v_sub_f32_e32 v41, v114, v106
	v_lshlrev_b64 v[54:55], 11, v[54:55]
	v_min_f32_e32 v41, 0x42a00000, v41
	v_lshl_add_u64 v[54:55], v[44:45], 0, v[54:55]
	v_mul_f32_e32 v41, 0x3fb8aa3b, v41
	global_store_dword v[54:55], v61, off
	v_exp_f32_e32 v54, v41
	v_sub_f32_e32 v41, v106, v114
	v_min_f32_e32 v41, 0x42a00000, v41
	v_mul_f32_e32 v41, 0x3fb8aa3b, v41
	v_exp_f32_e32 v104, v41
	v_mul_f32_e32 v41, 0x3fb8aa3b, v114
	v_exp_f32_e32 v106, v41
	v_add_f32_e32 v41, v94, v114
	v_mul_f32_e32 v41, 0x3fb8aa3b, v41
	v_exp_f32_e32 v108, v41
	v_sub_f32_e32 v41, v64, v107
	v_min_f32_e32 v41, 0x42a00000, v41
	v_mul_f32_e32 v41, 0x3fb8aa3b, v41
	v_exp_f32_e32 v55, v41
	v_mul_f32_e32 v41, 0xbfb8aa3b, v50
	v_exp_f32_e32 v41, v41
	v_sub_f32_e32 v39, v96, v39
	v_mul_f32_e32 v39, 0x3fb8aa3b, v39
	v_sub_f32_e32 v37, v96, v37
	v_add_f32_e32 v41, 1.0, v41
	v_rcp_f32_e32 v112, v41
	v_mul_f32_e32 v41, 0xbfb8aa3b, v51
	v_exp_f32_e32 v41, v41
	v_exp_f32_e32 v127, v39
	v_mul_f32_e32 v60, 0x3fb8aa3b, v60
	v_mul_f32_e32 v37, 0x3fb8aa3b, v37
	v_add_f32_e32 v41, 1.0, v41
	v_rcp_f32_e32 v113, v41
	v_sub_f32_e32 v41, v107, v64
	v_min_f32_e32 v41, 0x42a00000, v41
	v_mul_f32_e32 v41, 0x3fb8aa3b, v41
	v_exp_f32_e32 v105, v41
	v_mul_f32_e32 v41, 0x3fb8aa3b, v64
	v_exp_f32_e32 v107, v41
	v_add_f32_e32 v41, v95, v64
	v_mul_f32_e32 v41, 0x3fb8aa3b, v41
	v_pk_mul_f32 v[50:51], v[112:113], v[50:51]
	v_exp_f32_e32 v109, v41
	v_pk_mul_f32 v[54:55], v[50:51], v[54:55]
	v_pk_mul_f32 v[48:49], v[56:57], v[104:105]
	v_cvt_pk_bf16_f32 v41, v54, v55
	v_pk_mul_f32 v[104:105], v[50:51], v[106:107]
	ds_write_b32 v205, v41 offset:5728
	v_cvt_pk_bf16_f32 v41, v48, v49
	v_lshl_add_u64 v[48:49], s[46:47], 0, v[82:83]
	v_pk_mul_f32 v[50:51], v[50:51], v[108:109]
	ds_write_b32 v205, v41 offset:23136
	v_cvt_pk_bf16_f32 v41, v104, v105
	v_lshlrev_b64 v[48:49], 11, v[48:49]
	ds_write_b32 v206, v41 offset:1632
	v_cvt_pk_bf16_f32 v41, v50, v51
	v_lshl_add_u64 v[44:45], v[44:45], 0, v[48:49]
	global_store_dword v[44:45], v41, off
	v_sub_f32_e32 v44, v97, v64
	v_mul_f32_e32 v44, 0x3fb8aa3b, v44
	v_exp_f32_e32 v111, v44
	v_mov_b32_e32 v44, v59
	v_mov_b32_e32 v45, v53
	v_pk_mul_f32 v[44:45], v[44:45], v[98:99]
	v_exp_f32_e32 v60, v60
	v_cvt_pk_bf16_f32 v48, v44, v45
	v_mov_b32_e32 v44, v101
	v_mov_b32_e32 v45, v57
	v_pk_mul_f32 v[44:45], v[44:45], v[110:111]
	v_and_b32_e32 v103, 0xffff, v200
	v_cvt_pk_bf16_f32 v44, v44, v45
	v_and_b32_e32 v45, 0xffff0000, v44
	v_lshlrev_b32_e32 v44, 16, v44
	v_or_b32_sdwa v49, v45, v48 dst_sel:DWORD dst_unused:UNUSED_PAD src0_sel:DWORD src1_sel:WORD_1
	v_or_b32_sdwa v48, v44, v48 dst_sel:DWORD dst_unused:UNUSED_PAD src0_sel:DWORD src1_sel:WORD_0
	v_sub_f32_e32 v44, v96, v114
	v_exp_f32_e32 v61, v37
	v_mul_f32_e32 v44, 0x3fb8aa3b, v44
	v_lshl_or_b32 v41, v93, 16, v103
	v_exp_f32_e32 v103, v44
	v_cvt_pk_bf16_f32 v39, v42, v43
	v_mov_b32_e32 v42, v122
	v_mov_b32_e32 v43, v210
	v_pk_mul_f32 v[42:43], v[42:43], v[126:127]
	v_mov_b32_e32 v59, v52
	v_cvt_pk_bf16_f32 v42, v42, v43
	v_pk_mul_f32 v[44:45], v[58:59], v[60:61]
	v_mov_b32_e32 v101, v56
	v_and_b32_e32 v43, 0xffff0000, v42
	v_lshlrev_b32_e32 v42, 16, v42
	v_mov_b32_e32 v210, v123
	v_cvt_pk_bf16_f32 v50, v44, v45
	v_pk_mul_f32 v[44:45], v[100:101], v[102:103]
	v_or_b32_sdwa v43, v43, v39 dst_sel:DWORD dst_unused:UNUSED_PAD src0_sel:DWORD src1_sel:WORD_1
	v_or_b32_sdwa v42, v42, v39 dst_sel:DWORD dst_unused:UNUSED_PAD src0_sel:DWORD src1_sel:WORD_0
	v_cvt_pk_bf16_f32 v39, v46, v47
	v_pk_mul_f32 v[46:47], v[210:211], v[124:125]
	v_cvt_pk_bf16_f32 v44, v44, v45
	v_cvt_pk_bf16_f32 v46, v46, v47
	v_and_b32_e32 v45, 0xffff0000, v44
	v_lshlrev_b32_e32 v44, 16, v44
	v_and_b32_e32 v47, 0xffff0000, v46
	v_lshlrev_b32_e32 v46, 16, v46
	v_lshrrev_b32_e32 v37, 16, v200
	v_or_b32_sdwa v45, v45, v50 dst_sel:DWORD dst_unused:UNUSED_PAD src0_sel:DWORD src1_sel:WORD_1
	v_or_b32_sdwa v44, v44, v50 dst_sel:DWORD dst_unused:UNUSED_PAD src0_sel:DWORD src1_sel:WORD_0
	v_or_b32_sdwa v47, v47, v39 dst_sel:DWORD dst_unused:UNUSED_PAD src0_sel:DWORD src1_sel:WORD_1
	v_or_b32_sdwa v46, v46, v39 dst_sel:DWORD dst_unused:UNUSED_PAD src0_sel:DWORD src1_sel:WORD_0
	v_lshl_or_b32 v39, v203, 16, v207
	v_and_or_b32 v35, v203, s60, v35
	v_and_or_b32 v37, v93, s60, v37
	ds_write_b128 v85, v[42:45] offset:38912
	ds_write_b128 v85, v[38:41] offset:57344
	ds_write_b128 v85, v[46:49] offset:39056
	ds_write_b128 v85, v[34:37] offset:57488
	s_and_saveexec_b64 s[0:1], s[4:5]
	s_cbranch_execz .LBB0_578
	v_mul_f32_e32 v34, 0x3fb8aa3b, v96
	v_mul_f32_e32 v35, 0x3fb8aa3b, v97
	v_exp_f32_e32 v34, v34
	v_exp_f32_e32 v35, v35
	v_add_u32_e32 v36, 0, v84
	v_add_u32_e32 v36, 0x21800, v36
	ds_write_b64 v36, v[34:35]

; template <int XSRC, bool HAS_F, bool HAS_NEXT, bool SPLIT, int XDST  > ...
;     ...
;             if (SPLIT && row >= MP) {
; #pragma unroll
;                 for (int i = 0; i < 8; ++i) { const float* pr = part + (size_t)(row - MP) * DM + (i >> 1) * 512 + lane * 8 + (i & 1) * 4; f32x4 a = *(const f32x4*)pr;
; #pragma unroll
;                     for (int s = 1; s < 8; ++s) a = a + *(const f32x4*)(pr + (size_t)s * 1024 * DM);
;                     f[i] = a; __builtin_amdgcn_sched_barrier(0); } }
.LBB0_967:
	s_addk_i32 s0, 0xc000
	s_lshl_b64 s[12:13], s[0:1], 13
	v_lshl_add_u64 v[82:83], v[102:103], 0, s[12:13]
	s_mov_b32 s12, 0x800000
	s_mov_b32 s13, 0
	v_lshl_add_u64 v[84:85], v[82:83], 0, s[12:13]
	v_lshl_add_u64 v[86:87], v[84:85], 0, s[12:13]
	v_lshl_add_u64 v[88:89], v[86:87], 0, s[12:13]
	v_lshl_add_u64 v[90:91], v[88:89], 0, s[12:13]
	v_lshl_add_u64 v[92:93], v[90:91], 0, s[12:13]
	v_lshl_add_u64 v[94:95], v[92:93], 0, s[12:13]
	v_lshl_add_u64 v[96:97], v[94:95], 0, s[12:13]
	global_load_dwordx4 v[6:9], v[82:83], off
	global_load_dwordx4 v[10:13], v[84:85], off
	global_load_dwordx4 v[14:17], v[86:87], off
	global_load_dwordx4 v[18:21], v[88:89], off
	global_load_dwordx4 v[22:25], v[90:91], off
	global_load_dwordx4 v[26:29], v[92:93], off
	global_load_dwordx4 v[30:33], v[94:95], off
	global_load_dwordx4 v[34:37], v[96:97], off
	s_waitcnt vmcnt(6)
	v_pk_add_f32 v[56:57], v[8:9], v[12:13]
	v_pk_add_f32 v[54:55], v[6:7], v[10:11]
	s_waitcnt vmcnt(5)
	v_pk_add_f32 v[56:57], v[56:57], v[16:17]
	v_pk_add_f32 v[54:55], v[54:55], v[14:15]
	s_waitcnt vmcnt(4)
	v_pk_add_f32 v[56:57], v[56:57], v[20:21]
	v_pk_add_f32 v[54:55], v[54:55], v[18:19]
	s_waitcnt vmcnt(3)
	v_pk_add_f32 v[56:57], v[56:57], v[24:25]
	v_pk_add_f32 v[54:55], v[54:55], v[22:23]
	s_waitcnt vmcnt(2)
	v_pk_add_f32 v[56:57], v[56:57], v[28:29]
	v_pk_add_f32 v[54:55], v[54:55], v[26:27]
	s_waitcnt vmcnt(1)
	v_pk_add_f32 v[56:57], v[56:57], v[32:33]
	v_pk_add_f32 v[54:55], v[54:55], v[30:31]
	s_waitcnt vmcnt(0)
	v_pk_add_f32 v[56:57], v[56:57], v[36:37]
	v_pk_add_f32 v[54:55], v[54:55], v[34:35]
	global_load_dwordx4 v[6:9], v[82:83], off offset:16
	global_load_dwordx4 v[10:13], v[84:85], off offset:16
	global_load_dwordx4 v[14:17], v[86:87], off offset:16
	global_load_dwordx4 v[18:21], v[88:89], off offset:16
	global_load_dwordx4 v[22:25], v[90:91], off offset:16
	global_load_dwordx4 v[26:29], v[92:93], off offset:16
	global_load_dwordx4 v[30:33], v[94:95], off offset:16
	global_load_dwordx4 v[34:37], v[96:97], off offset:16
	s_waitcnt vmcnt(6)
	v_pk_add_f32 v[60:61], v[8:9], v[12:13]
	v_pk_add_f32 v[58:59], v[6:7], v[10:11]
	s_waitcnt vmcnt(5)
	v_pk_add_f32 v[60:61], v[60:61], v[16:17]
	v_pk_add_f32 v[58:59], v[58:59], v[14:15]
	s_waitcnt vmcnt(4)
	v_pk_add_f32 v[60:61], v[60:61], v[20:21]
	v_pk_add_f32 v[58:59], v[58:59], v[18:19]
	s_waitcnt vmcnt(3)
	v_pk_add_f32 v[60:61], v[60:61], v[24:25]
	v_pk_add_f32 v[58:59], v[58:59], v[22:23]
	s_waitcnt vmcnt(2)
	v_pk_add_f32 v[60:61], v[60:61], v[28:29]
	v_pk_add_f32 v[58:59], v[58:59], v[26:27]
	s_waitcnt vmcnt(1)
	v_pk_add_f32 v[60:61], v[60:61], v[32:33]
	v_pk_add_f32 v[58:59], v[58:59], v[30:31]
	s_waitcnt vmcnt(0)
	v_pk_add_f32 v[60:61], v[60:61], v[36:37]
	v_pk_add_f32 v[58:59], v[58:59], v[34:35]
	global_load_dwordx4 v[6:9], v[82:83], off offset:2048
	global_load_dwordx4 v[10:13], v[84:85], off offset:2048
	global_load_dwordx4 v[14:17], v[86:87], off offset:2048
	global_load_dwordx4 v[18:21], v[88:89], off offset:2048
	global_load_dwordx4 v[22:25], v[90:91], off offset:2048
	global_load_dwordx4 v[26:29], v[92:93], off offset:2048
	global_load_dwordx4 v[30:33], v[94:95], off offset:2048
	global_load_dwordx4 v[34:37], v[96:97], off offset:2048
	s_waitcnt vmcnt(6)
	v_pk_add_f32 v[64:65], v[8:9], v[12:13]
	v_pk_add_f32 v[62:63], v[6:7], v[10:11]
	s_waitcnt vmcnt(5)
	v_pk_add_f32 v[64:65], v[64:65], v[16:17]
	v_pk_add_f32 v[62:63], v[62:63], v[14:15]
	s_waitcnt vmcnt(4)
	v_pk_add_f32 v[64:65], v[64:65], v[20:21]
	v_pk_add_f32 v[62:63], v[62:63], v[18:19]
	s_waitcnt vmcnt(3)
	v_pk_add_f32 v[64:65], v[64:65], v[24:25]
	v_pk_add_f32 v[62:63], v[62:63], v[22:23]
	s_waitcnt vmcnt(2)
	v_pk_add_f32 v[64:65], v[64:65], v[28:29]
	v_pk_add_f32 v[62:63], v[62:63], v[26:27]
	s_waitcnt vmcnt(1)
	v_pk_add_f32 v[64:65], v[64:65], v[32:33]
	v_pk_add_f32 v[62:63], v[62:63], v[30:31]
	s_waitcnt vmcnt(0)
	v_pk_add_f32 v[64:65], v[64:65], v[36:37]
	v_pk_add_f32 v[62:63], v[62:63], v[34:35]
	global_load_dwordx4 v[6:9], v[82:83], off offset:2064
	global_load_dwordx4 v[10:13], v[84:85], off offset:2064
	global_load_dwordx4 v[14:17], v[86:87], off offset:2064
	global_load_dwordx4 v[18:21], v[88:89], off offset:2064
	global_load_dwordx4 v[22:25], v[90:91], off offset:2064
	global_load_dwordx4 v[26:29], v[92:93], off offset:2064
	global_load_dwordx4 v[30:33], v[94:95], off offset:2064
	global_load_dwordx4 v[34:37], v[96:97], off offset:2064
	s_waitcnt vmcnt(6)
	v_pk_add_f32 v[68:69], v[8:9], v[12:13]
	v_pk_add_f32 v[66:67], v[6:7], v[10:11]
	s_waitcnt vmcnt(5)
	v_pk_add_f32 v[68:69], v[68:69], v[16:17]
	v_pk_add_f32 v[66:67], v[66:67], v[14:15]
	s_waitcnt vmcnt(4)
	v_pk_add_f32 v[68:69], v[68:69], v[20:21]
	v_pk_add_f32 v[66:67], v[66:67], v[18:19]
	s_waitcnt vmcnt(3)
	v_pk_add_f32 v[68:69], v[68:69], v[24:25]
	v_pk_add_f32 v[66:67], v[66:67], v[22:23]
	s_waitcnt vmcnt(2)
	v_pk_add_f32 v[68:69], v[68:69], v[28:29]
	v_pk_add_f32 v[66:67], v[66:67], v[26:27]
	s_waitcnt vmcnt(1)
	v_pk_add_f32 v[68:69], v[68:69], v[32:33]
	v_pk_add_f32 v[66:67], v[66:67], v[30:31]
	s_waitcnt vmcnt(0)
; template <int XSRC, bool HAS_F, bool HAS_NEXT, bool SPLIT, int XDST  > ...
;     ...
;             if (SPLIT && row >= MP) {
; #pragma unroll
;                 for (int i = 0; i < 8; ++i) { const float* pr = part + (size_t)(row - MP) * DM + (i >> 1) * 512 + lane * 8 + (i & 1) * 4; f32x4 a = *(const f32x4*)pr;
; #pragma unroll
;                     for (int s = 1; s < 8; ++s) a = a + *(const f32x4*)(pr + (size_t)s * 1024 * DM);
;                     f[i] = a; __builtin_amdgcn_sched_barrier(0); } }
	v_pk_add_f32 v[68:69], v[68:69], v[36:37]
	v_pk_add_f32 v[66:67], v[66:67], v[34:35]
	s_movk_i32 s12, 0x1000
	v_lshl_add_u64 v[82:83], v[82:83], 0, s[12:13]
	v_lshl_add_u64 v[84:85], v[84:85], 0, s[12:13]
	v_lshl_add_u64 v[86:87], v[86:87], 0, s[12:13]
	v_lshl_add_u64 v[88:89], v[88:89], 0, s[12:13]
	v_lshl_add_u64 v[90:91], v[90:91], 0, s[12:13]
	v_lshl_add_u64 v[92:93], v[92:93], 0, s[12:13]
	v_lshl_add_u64 v[94:95], v[94:95], 0, s[12:13]
	v_lshl_add_u64 v[96:97], v[96:97], 0, s[12:13]
	global_load_dwordx4 v[6:9], v[82:83], off
	global_load_dwordx4 v[10:13], v[84:85], off
	global_load_dwordx4 v[14:17], v[86:87], off
	global_load_dwordx4 v[18:21], v[88:89], off
	global_load_dwordx4 v[22:25], v[90:91], off
	global_load_dwordx4 v[26:29], v[92:93], off
	global_load_dwordx4 v[30:33], v[94:95], off
	global_load_dwordx4 v[34:37], v[96:97], off
	s_waitcnt vmcnt(6)
	v_pk_add_f32 v[72:73], v[8:9], v[12:13]
	v_pk_add_f32 v[70:71], v[6:7], v[10:11]
	s_waitcnt vmcnt(5)
	v_pk_add_f32 v[72:73], v[72:73], v[16:17]
	v_pk_add_f32 v[70:71], v[70:71], v[14:15]
	s_waitcnt vmcnt(4)
	v_pk_add_f32 v[72:73], v[72:73], v[20:21]
	v_pk_add_f32 v[70:71], v[70:71], v[18:19]
	s_waitcnt vmcnt(3)
	v_pk_add_f32 v[72:73], v[72:73], v[24:25]
	v_pk_add_f32 v[70:71], v[70:71], v[22:23]
	s_waitcnt vmcnt(2)
	v_pk_add_f32 v[72:73], v[72:73], v[28:29]
	v_pk_add_f32 v[70:71], v[70:71], v[26:27]
	s_waitcnt vmcnt(1)
	v_pk_add_f32 v[72:73], v[72:73], v[32:33]
	v_pk_add_f32 v[70:71], v[70:71], v[30:31]
	s_waitcnt vmcnt(0)
	v_pk_add_f32 v[72:73], v[72:73], v[36:37]
	v_pk_add_f32 v[70:71], v[70:71], v[34:35]
	global_load_dwordx4 v[6:9], v[82:83], off offset:16
	global_load_dwordx4 v[10:13], v[84:85], off offset:16
	global_load_dwordx4 v[14:17], v[86:87], off offset:16
	global_load_dwordx4 v[18:21], v[88:89], off offset:16
	global_load_dwordx4 v[22:25], v[90:91], off offset:16
	global_load_dwordx4 v[26:29], v[92:93], off offset:16
	global_load_dwordx4 v[30:33], v[94:95], off offset:16
	global_load_dwordx4 v[34:37], v[96:97], off offset:16
	s_waitcnt vmcnt(6)
	v_pk_add_f32 v[76:77], v[8:9], v[12:13]
	v_pk_add_f32 v[74:75], v[6:7], v[10:11]
	s_waitcnt vmcnt(5)
	v_pk_add_f32 v[76:77], v[76:77], v[16:17]
	v_pk_add_f32 v[74:75], v[74:75], v[14:15]
	s_waitcnt vmcnt(4)
	v_pk_add_f32 v[76:77], v[76:77], v[20:21]
	v_pk_add_f32 v[74:75], v[74:75], v[18:19]
	s_waitcnt vmcnt(3)
	v_pk_add_f32 v[76:77], v[76:77], v[24:25]
	v_pk_add_f32 v[74:75], v[74:75], v[22:23]
	s_waitcnt vmcnt(2)
	v_pk_add_f32 v[76:77], v[76:77], v[28:29]
	v_pk_add_f32 v[74:75], v[74:75], v[26:27]
	s_waitcnt vmcnt(1)
	v_pk_add_f32 v[76:77], v[76:77], v[32:33]
	v_pk_add_f32 v[74:75], v[74:75], v[30:31]
	s_waitcnt vmcnt(0)
	v_pk_add_f32 v[76:77], v[76:77], v[36:37]
	v_pk_add_f32 v[74:75], v[74:75], v[34:35]
	global_load_dwordx4 v[6:9], v[82:83], off offset:2048
	global_load_dwordx4 v[10:13], v[84:85], off offset:2048
	global_load_dwordx4 v[14:17], v[86:87], off offset:2048
	global_load_dwordx4 v[18:21], v[88:89], off offset:2048
	global_load_dwordx4 v[22:25], v[90:91], off offset:2048
	global_load_dwordx4 v[26:29], v[92:93], off offset:2048
	global_load_dwordx4 v[30:33], v[94:95], off offset:2048
	global_load_dwordx4 v[34:37], v[96:97], off offset:2048
	s_waitcnt vmcnt(6)
	v_pk_add_f32 v[80:81], v[8:9], v[12:13]
	v_pk_add_f32 v[78:79], v[6:7], v[10:11]
	s_waitcnt vmcnt(5)
	v_pk_add_f32 v[80:81], v[80:81], v[16:17]
	v_pk_add_f32 v[78:79], v[78:79], v[14:15]
	s_waitcnt vmcnt(4)
	v_pk_add_f32 v[80:81], v[80:81], v[20:21]
	v_pk_add_f32 v[78:79], v[78:79], v[18:19]
	s_waitcnt vmcnt(3)
	v_pk_add_f32 v[80:81], v[80:81], v[24:25]
	v_pk_add_f32 v[78:79], v[78:79], v[22:23]
	s_waitcnt vmcnt(2)
	v_pk_add_f32 v[80:81], v[80:81], v[28:29]
	v_pk_add_f32 v[78:79], v[78:79], v[26:27]
	s_waitcnt vmcnt(1)
	v_pk_add_f32 v[80:81], v[80:81], v[32:33]
	v_pk_add_f32 v[78:79], v[78:79], v[30:31]
	s_waitcnt vmcnt(0)
	v_pk_add_f32 v[80:81], v[80:81], v[36:37]
	v_pk_add_f32 v[78:79], v[78:79], v[34:35]
	global_load_dwordx4 v[6:9], v[82:83], off offset:2064
	global_load_dwordx4 v[10:13], v[84:85], off offset:2064
	global_load_dwordx4 v[14:17], v[86:87], off offset:2064
	global_load_dwordx4 v[18:21], v[88:89], off offset:2064
	global_load_dwordx4 v[22:25], v[90:91], off offset:2064
	global_load_dwordx4 v[26:29], v[92:93], off offset:2064
	global_load_dwordx4 v[30:33], v[94:95], off offset:2064
	global_load_dwordx4 v[34:37], v[96:97], off offset:2064
	s_waitcnt vmcnt(6)
	v_pk_add_f32 v[100:101], v[8:9], v[12:13]
	v_pk_add_f32 v[98:99], v[6:7], v[10:11]
	s_waitcnt vmcnt(5)
	v_pk_add_f32 v[100:101], v[100:101], v[16:17]
	v_pk_add_f32 v[98:99], v[98:99], v[14:15]
	s_waitcnt vmcnt(4)
	v_pk_add_f32 v[100:101], v[100:101], v[20:21]
	v_pk_add_f32 v[98:99], v[98:99], v[18:19]
	s_waitcnt vmcnt(3)
	v_pk_add_f32 v[100:101], v[100:101], v[24:25]
	v_pk_add_f32 v[98:99], v[98:99], v[22:23]
	s_waitcnt vmcnt(2)
	v_pk_add_f32 v[100:101], v[100:101], v[28:29]
	v_pk_add_f32 v[98:99], v[98:99], v[26:27]
	s_waitcnt vmcnt(1)
	v_pk_add_f32 v[100:101], v[100:101], v[32:33]
	v_pk_add_f32 v[98:99], v[98:99], v[30:31]
	s_waitcnt vmcnt(0)
	v_pk_add_f32 v[100:101], v[100:101], v[36:37]
	v_pk_add_f32 v[98:99], v[98:99], v[34:35]
	v_mov_b64_e32 v[6:7], 0
	v_mov_b64_e32 v[8:9], 0
	v_mov_b64_e32 v[10:11], 0
	v_mov_b64_e32 v[12:13], 0
	v_mov_b64_e32 v[14:15], 0
	v_mov_b64_e32 v[16:17], 0
	v_mov_b64_e32 v[18:19], 0
	v_mov_b64_e32 v[20:21], 0
	v_mov_b64_e32 v[22:23], 0
	v_mov_b64_e32 v[24:25], 0
	v_mov_b64_e32 v[26:27], 0
	v_mov_b64_e32 v[28:29], 0
	v_mov_b64_e32 v[30:31], 0
	v_mov_b64_e32 v[32:33], 0
	v_mov_b64_e32 v[34:35], 0
	v_mov_b64_e32 v[36:37], 0
	s_branch .LBB0_959
